# v72 + attention step loops: 182 SLP-packed v_pk_add_f32 (row sums, bias adds) split into scalar v_add_f32 pairs, bit-identical; packed f32 beside MFMAs is a documented anti-lever
# baseline (speedup 1.0000x reference)
; #define LAS __attribute__((address_space(3)))
; template <bool MOBA>
; __device__ __forceinline__ void attn_unit(unsigned char* lds, LAS unsigned char* lds3, const Params& p, int b, int h, int qb) {
;     ...
;         if (active) {
;             const bool diag = (tl == (w >> 1));
;             f32x4 s[4][2];
;             bool band = false;
;             if (!MOBA) {
;                 const float f0 = fq2[0] - mref[0], f1 = fq2[1] - mref[1];
; #pragma unroll
;                 for (int kb = 0; kb < 4; ++kb) { const f32x4 fk = *(const LAS f32x4*)(Fs + 64 * t + 16 * kb + 4 * fq); s[kb][0] = f0 - fk; s[kb][1] = f1 - fk; }
;             } else {
;                 band = (t >> 2) >= qb - 1;
;                 const float cc = band ? 0.f : c31;
;                 const float c0 = (qv[0] ? cc : NEGBIG) - mrc[0], c1 = (qv[1] ? cc : NEGBIG) - mrc[1];
; #pragma unroll
;                 for (int kb = 0; kb < 4; ++kb) { s[kb][0] = (f32x4){c0, c0, c0, c0}; s[kb][1] = (f32x4){c1, c1, c1, c1}; }
;             }
;             { bf16x8 kf[4][2];
; #pragma unroll
;             for (int kb = 0; kb < 4; ++kb)
; #pragma unroll
;                 for (int ks = 0; ks < 2; ++ks) kf[kb][ks] = *(const LAS bf16x8*)(Ks + slot * 4608 + (16 * kb + fr) * 72 + 32 * ks + 8 * fq);
;             __builtin_amdgcn_sched_barrier(0);
; #pragma unroll
;             for (int kb = 0; kb < 4; ++kb)
; #pragma unroll
;                 for (int ks = 0; ks < 2; ++ks) {
;                     s[kb][0] = __builtin_amdgcn_mfma_f32_16x16x32_bf16(kf[kb][ks], qf[0][ks], s[kb][0], 0, 0, 0); s[kb][1] = __builtin_amdgcn_mfma_f32_16x16x32_bf16(kf[kb][ks], qf[1][ks], s[kb][1], 0, 0, 0); }
;             __builtin_amdgcn_sched_barrier(0); }
;             if (MOBA && band) {
;                 asm volatile("" ::: "memory");
; #pragma unroll
;                 for (int kb = 0; kb < 4; ++kb)
; #pragma unroll
;                     for (int jb = 0; jb < 2; ++jb)
; #pragma unroll
;                         for (int r = 0; r < 4; ++r) { int d = (256 * qb + qpl[jb]) - (64 * t + 16 * kb + 4 * fq + r); d = d < 0 ? 0 : (d > 127 ? 127 : d); s[kb][jb][r] += tbl[d]; }
.LBB0_435:
	v_lshlrev_b32_e32 v3, 1, v1
	v_and_b32_e32 v52, 24, v3
	v_and_b32_e32 v53, 3, v104
	v_mul_u32_u24_e32 v140, 0x90, v1
	v_or_b32_e32 v1, v52, v53
	v_add_u32_e32 v138, 0, v2
	v_lshlrev_b32_e32 v2, 2, v168
	v_mul_u32_u24_e32 v157, 0x90, v1
	v_or_b32_e32 v1, 4, v53
	v_bitop3_b32 v156, v3, v2, 24 bitop3:0x6c
	v_or_b32_e32 v3, v52, v1
	v_mul_u32_u24_e32 v159, 0x90, v3
	v_or_b32_e32 v3, 32, v52
	s_sub_i32 s4, s42, 32
	v_mul_i32_i24_e32 v139, -4, v168
	v_lshl_or_b32 v141, s21, 6, v2
	v_or_b32_e32 v53, v3, v53
	v_bitop3_b32 v160, v52, v2, 32 bitop3:0x36
	v_or_b32_e32 v1, v3, v1
	v_bitop3_b32 v164, v2, v52, 32 bitop3:0x36
	v_bitop3_b32 v166, v52, v2, 32 bitop3:0x14
	v_mad_i32_i24 v169, v168, -4, s4
	s_sub_i32 s4, s42, 48
	v_or_b32_e32 v142, 2, v141
	v_or_b32_e32 v143, 3, v141
	v_or_b32_e32 v144, 16, v141
	v_or_b32_e32 v145, 17, v141
	v_or_b32_e32 v146, 18, v141
	v_or_b32_e32 v147, 19, v141
	v_or_b32_e32 v148, 32, v141
	v_or_b32_e32 v149, 33, v141
	v_or_b32_e32 v150, 34, v141
	v_or_b32_e32 v151, 35, v141
	v_or_b32_e32 v152, 48, v141
	v_or_b32_e32 v153, 49, v141
	v_or_b32_e32 v154, 50, v141
	v_or_b32_e32 v155, 51, v141
	v_xor_b32_e32 v158, 16, v156
	v_mul_u32_u24_e32 v161, 0x90, v53
	v_xor_b32_e32 v162, 16, v160
	v_mul_u32_u24_e32 v163, 0x90, v1
	v_xor_b32_e32 v165, 16, v164
	v_xor_b32_e32 v167, 16, v166
	v_add3_u32 v128, s42, -16, v139
	v_mad_i32_i24 v105, v168, -4, s4
	s_andn2_b64 vcc, exec, s[6:7]
	v_add_u32_e32 v84, v138, v140
	v_cndmask_b32_e64 v85, v226, 0, s[10:11]
	v_cndmask_b32_e64 v86, v226, 0, s[12:13]
	s_cbranch_vccnz .LBB0_439
	ds_read_b128 v[60:63], v84
	ds_read_b128 v[64:67], v84 offset:64
	ds_read_b128 v[68:71], v84 offset:2304
	ds_read_b128 v[72:75], v84 offset:2368
	ds_read_b128 v[76:79], v84 offset:4608
	ds_read_b128 v[80:83], v84 offset:4672
	ds_read_b128 v[88:91], v84 offset:6912
	ds_read_b128 v[92:95], v84 offset:6976
	v_sub_f32_e32 v52, v85, v122
	s_waitcnt lgkmcnt(8)
	v_sub_f32_e32 v56, v86, v123
	v_mov_b32_e32 v53, v52
	v_mov_b32_e32 v54, v52
	v_mov_b32_e32 v55, v52
	v_mov_b32_e32 v57, v56
	v_mov_b32_e32 v58, v56
	v_mov_b32_e32 v59, v56
	s_waitcnt lgkmcnt(7)
	v_mfma_f32_16x16x32_bf16 v[96:99], v[60:63], v[8:11], v[52:55]
	s_lshl_b32 s5, s44, 6
	s_add_i32 s4, 0, 0x13000
	s_cmp_lg_u32 s16, s21
	v_mfma_f32_16x16x32_bf16 v[60:63], v[60:63], v[16:19], v[56:59]
	s_waitcnt lgkmcnt(6)
	v_mfma_f32_16x16x32_bf16 v[96:99], v[64:67], v[4:7], v[96:99]
	v_mfma_f32_16x16x32_bf16 v[100:103], v[64:67], v[12:15], v[60:63]
	s_waitcnt lgkmcnt(5)
	v_mfma_f32_16x16x32_bf16 v[60:63], v[68:71], v[8:11], v[52:55]
	v_mfma_f32_16x16x32_bf16 v[64:67], v[68:71], v[16:19], v[56:59]
	s_waitcnt lgkmcnt(4)
	v_mfma_f32_16x16x32_bf16 v[110:113], v[72:75], v[4:7], v[60:63]
	v_mfma_f32_16x16x32_bf16 v[68:71], v[72:75], v[12:15], v[64:67]
	s_waitcnt lgkmcnt(3)
	v_mfma_f32_16x16x32_bf16 v[60:63], v[76:79], v[8:11], v[52:55]
	v_mfma_f32_16x16x32_bf16 v[72:75], v[76:79], v[16:19], v[56:59]
	s_waitcnt lgkmcnt(2)
	v_mfma_f32_16x16x32_bf16 v[64:67], v[80:83], v[4:7], v[60:63]
	v_mfma_f32_16x16x32_bf16 v[60:63], v[80:83], v[12:15], v[72:75]
	s_waitcnt lgkmcnt(1)
	v_mfma_f32_16x16x32_bf16 v[52:55], v[88:91], v[8:11], v[52:55]
	v_mfma_f32_16x16x32_bf16 v[72:75], v[88:91], v[16:19], v[56:59]
	s_waitcnt lgkmcnt(0)
	v_mfma_f32_16x16x32_bf16 v[56:59], v[92:95], v[4:7], v[52:55]
	v_mfma_f32_16x16x32_bf16 v[52:55], v[92:95], v[12:15], v[72:75]
	v_subrev_u32_e32 v1, s5, v139
	v_add_u32_e32 v1, s42, v1
	v_add_u32_e32 v3, v124, v1
	v_add_u32_e32 v1, v125, v1
	v_med3_i32 v2, v3, 0, v227
	v_med3_i32 v74, v1, 0, v227
	v_lshl_add_u32 v2, v2, 2, s4
	v_lshl_add_u32 v74, v74, 2, s4
	ds_read_b32 v72, v2
	ds_read_b32 v76, v74
	v_add_u32_e32 v74, -1, v1
	v_med3_i32 v74, v74, 0, v227
	v_lshl_add_u32 v74, v74, 2, s4
	ds_read_b32 v77, v74
	v_add_u32_e32 v74, -2, v1
	v_add_u32_e32 v1, -3, v1
	v_med3_i32 v1, v1, 0, v227
	v_lshl_add_u32 v1, v1, 2, s4
	ds_read_b32 v75, v1
	v_subrev_u32_e32 v1, s5, v128
	v_add_u32_e32 v79, v124, v1
	v_add_u32_e32 v1, v125, v1
	v_add_u32_e32 v2, -1, v3
	v_add_u32_e32 v83, -1, v1
	v_med3_i32 v2, v2, 0, v227
	v_med3_i32 v74, v74, 0, v227
	v_med3_i32 v82, v1, 0, v227
	v_med3_i32 v83, v83, 0, v227
	v_lshl_add_u32 v2, v2, 2, s4
	v_lshl_add_u32 v74, v74, 2, s4
	v_lshl_add_u32 v82, v82, 2, s4
	v_lshl_add_u32 v83, v83, 2, s4
	ds_read_b32 v73, v2
	ds_read_b32 v74, v74
	ds_read_b32 v82, v82
	ds_read_b32 v83, v83
	v_add_u32_e32 v87, -2, v1
	v_add_u32_e32 v1, -3, v1
	v_med3_i32 v87, v87, 0, v227
	v_med3_i32 v1, v1, 0, v227
	v_lshl_add_u32 v87, v87, 2, s4
	v_lshl_add_u32 v1, v1, 2, s4
	ds_read_b32 v88, v87
	ds_read_b32 v89, v1
	v_subrev_u32_e32 v1, s5, v169
	v_add_u32_e32 v87, v124, v1
	v_add_u32_e32 v2, -2, v3
	s_waitcnt lgkmcnt(2)
	v_add_f32_e32 v68, v68, v82
	v_add_f32_e32 v69, v69, v83
	v_add_u32_e32 v83, -1, v87
	v_med3_i32 v2, v2, 0, v227
	v_med3_i32 v78, v79, 0, v227
	v_med3_i32 v82, v87, 0, v227
	v_med3_i32 v83, v83, 0, v227
	v_lshl_add_u32 v2, v2, 2, s4
	v_lshl_add_u32 v78, v78, 2, s4
	v_lshl_add_u32 v82, v82, 2, s4
	v_lshl_add_u32 v83, v83, 2, s4
	ds_read_b32 v2, v2
	ds_read_b32 v80, v78
	ds_read_b32 v82, v82
	ds_read_b32 v83, v83
	s_waitcnt lgkmcnt(4)
	v_add_f32_e32 v70, v70, v88
	v_add_f32_e32 v71, v71, v89
	v_add_u32_e32 v88, -2, v87
	v_add_u32_e32 v87, -3, v87
	v_med3_i32 v88, v88, 0, v227
	v_med3_i32 v87, v87, 0, v227
	v_lshl_add_u32 v88, v88, 2, s4
	v_lshl_add_u32 v87, v87, 2, s4
	v_add_u32_e32 v1, v125, v1
	v_add_u32_e32 v3, -3, v3
	ds_read_b32 v88, v88
	ds_read_b32 v89, v87
	v_add_u32_e32 v78, -1, v79
	s_waitcnt lgkmcnt(2)
; template <bool MOBA>
; __device__ __forceinline__ void attn_unit(unsigned char* lds, LAS unsigned char* lds3, const Params& p, int b, int h, int qb) {
;     ...
;             if (MOBA && band) {
;                 asm volatile("" ::: "memory");
; #pragma unroll
;                 for (int kb = 0; kb < 4; ++kb)
; #pragma unroll
;                     for (int jb = 0; jb < 2; ++jb)
; #pragma unroll
;                         for (int r = 0; r < 4; ++r) { int d = (256 * qb + qpl[jb]) - (64 * t + 16 * kb + 4 * fq + r); d = d < 0 ? 0 : (d > 127 ? 127 : d); s[kb][jb][r] += tbl[d]; }
;             }
;             if (diag) {
;                 asm volatile("" ::: "memory");
; #pragma unroll
;                 for (int kb = 0; kb < 4; ++kb)
; #pragma unroll
;                     for (int jb = 0; jb < 2; ++jb)
; #pragma unroll
;                         for (int r = 0; r < 4; ++r) { if ((64 * tl + 16 * kb + 4 * fq + r) > (MOBA ? qpl[jb] : qloc + 16 * jb)) s[kb][jb][r] = NEGBIG; }
;             }
	v_add_f32_e32 v64, v64, v82
	v_add_f32_e32 v65, v65, v83
	v_add_u32_e32 v83, -1, v1
	v_med3_i32 v3, v3, 0, v227
	v_med3_i32 v78, v78, 0, v227
	v_med3_i32 v82, v1, 0, v227
	v_med3_i32 v83, v83, 0, v227
	v_lshl_add_u32 v3, v3, 2, s4
	v_lshl_add_u32 v78, v78, 2, s4
	v_lshl_add_u32 v82, v82, 2, s4
	v_lshl_add_u32 v83, v83, 2, s4
	ds_read_b32 v3, v3
	ds_read_b32 v81, v78
	ds_read_b32 v82, v82
	ds_read_b32 v83, v83
	v_add_u32_e32 v87, -2, v1
	v_add_u32_e32 v1, -3, v1
	v_med3_i32 v87, v87, 0, v227
	v_med3_i32 v1, v1, 0, v227
	v_lshl_add_u32 v87, v87, 2, s4
	v_lshl_add_u32 v1, v1, 2, s4
	s_waitcnt lgkmcnt(4)
	v_add_f32_e32 v66, v66, v88
	v_add_f32_e32 v67, v67, v89
	ds_read_b32 v88, v87
	ds_read_b32 v89, v1
	v_subrev_u32_e32 v1, s5, v105
	v_add_u32_e32 v87, v124, v1
	v_add_u32_e32 v78, -2, v79
	v_add_u32_e32 v79, -3, v79
	s_waitcnt lgkmcnt(2)
	v_add_f32_e32 v60, v60, v82
	v_add_f32_e32 v61, v61, v83
	v_add_u32_e32 v83, -1, v87
	v_med3_i32 v78, v78, 0, v227
	v_med3_i32 v79, v79, 0, v227
	v_med3_i32 v82, v87, 0, v227
	v_med3_i32 v83, v83, 0, v227
	v_lshl_add_u32 v78, v78, 2, s4
	v_lshl_add_u32 v79, v79, 2, s4
	v_lshl_add_u32 v82, v82, 2, s4
	v_lshl_add_u32 v83, v83, 2, s4
	ds_read_b32 v78, v78
	ds_read_b32 v79, v79
	ds_read_b32 v82, v82
	ds_read_b32 v83, v83
	s_waitcnt lgkmcnt(4)
	v_add_f32_e32 v62, v62, v88
	v_add_f32_e32 v63, v63, v89
	v_add_u32_e32 v88, -2, v87
	v_add_u32_e32 v87, -3, v87
	v_med3_i32 v88, v88, 0, v227
	v_med3_i32 v87, v87, 0, v227
	v_lshl_add_u32 v88, v88, 2, s4
	v_lshl_add_u32 v87, v87, 2, s4
	ds_read_b32 v88, v88
	ds_read_b32 v89, v87
	v_add_u32_e32 v1, v125, v1
	s_waitcnt lgkmcnt(2)
	v_add_f32_e32 v56, v56, v82
	v_add_f32_e32 v57, v57, v83
	v_med3_i32 v82, v1, 0, v227
	v_add_u32_e32 v83, -1, v1
	v_add_u32_e32 v87, -2, v1
	v_add_u32_e32 v1, -3, v1
	v_med3_i32 v83, v83, 0, v227
	v_med3_i32 v87, v87, 0, v227
	v_med3_i32 v1, v1, 0, v227
	v_lshl_add_u32 v82, v82, 2, s4
	v_lshl_add_u32 v83, v83, 2, s4
	v_lshl_add_u32 v87, v87, 2, s4
	v_lshl_add_u32 v1, v1, 2, s4
	s_waitcnt lgkmcnt(0)
	v_add_f32_e32 v58, v58, v88
	v_add_f32_e32 v59, v59, v89
	ds_read_b32 v82, v82
	ds_read_b32 v83, v83
	ds_read_b32 v88, v87
	ds_read_b32 v89, v1
	v_add_f32_e32 v2, v98, v2
	v_add_f32_e32 v3, v99, v3
	v_add_f32_e32 v72, v96, v72
	v_add_f32_e32 v73, v97, v73
	v_add_f32_e32 v74, v102, v74
	v_add_f32_e32 v75, v103, v75
	v_add_f32_e32 v76, v100, v76
	v_add_f32_e32 v77, v101, v77
	v_add_f32_e32 v78, v112, v78
	v_add_f32_e32 v79, v113, v79
	v_add_f32_e32 v80, v110, v80
	v_add_f32_e32 v81, v111, v81
	s_waitcnt lgkmcnt(0)
	v_add_f32_e32 v54, v54, v88
	v_add_f32_e32 v55, v55, v89
	v_add_f32_e32 v52, v52, v82
	v_add_f32_e32 v53, v53, v83
	s_cbranch_scc1 .LBB0_438
	v_mov_b32_e32 v82, s93
	v_cmp_gt_i32_e32 vcc, v141, v124
	s_nop 1
	v_cndmask_b32_e32 v1, v72, v82, vcc
	v_cmp_lt_i32_e32 vcc, v141, v124
	s_nop 1
	v_cndmask_b32_e32 v72, v1, v72, vcc
	v_cndmask_b32_e32 v73, v226, v73, vcc
	v_cmp_le_i32_e32 vcc, v142, v124
	s_nop 1
	v_cndmask_b32_e32 v2, v226, v2, vcc
	v_cmp_le_i32_e32 vcc, v143, v124
	s_nop 1
	v_cndmask_b32_e32 v3, v226, v3, vcc
	v_cmp_gt_i32_e32 vcc, v141, v125
	s_nop 1
	v_cndmask_b32_e32 v1, v76, v82, vcc
	v_cmp_lt_i32_e32 vcc, v141, v125
	s_nop 1
	v_cndmask_b32_e32 v76, v1, v76, vcc
	v_cndmask_b32_e32 v77, v226, v77, vcc
	v_cmp_le_i32_e32 vcc, v142, v125
	s_nop 1
	v_cndmask_b32_e32 v74, v226, v74, vcc
	v_cmp_le_i32_e32 vcc, v143, v125
	s_nop 1
	v_cndmask_b32_e32 v75, v226, v75, vcc
	v_cmp_gt_i32_e32 vcc, v144, v124
	s_nop 1
	v_cndmask_b32_e32 v80, v80, v82, vcc
	v_cmp_le_i32_e32 vcc, v145, v124
	s_nop 1
	v_cndmask_b32_e32 v81, v226, v81, vcc
	v_cmp_le_i32_e32 vcc, v146, v124
	s_nop 1
	v_cndmask_b32_e32 v78, v226, v78, vcc
	v_cmp_le_i32_e32 vcc, v147, v124
	s_nop 1
	v_cndmask_b32_e32 v79, v226, v79, vcc
	v_cmp_gt_i32_e32 vcc, v144, v125
	s_nop 1
	v_cndmask_b32_e32 v68, v68, v82, vcc
	v_cmp_le_i32_e32 vcc, v145, v125
	s_nop 1
	v_cndmask_b32_e32 v69, v226, v69, vcc
	v_cmp_le_i32_e32 vcc, v146, v125
	s_nop 1
	v_cndmask_b32_e32 v70, v226, v70, vcc
	v_cmp_le_i32_e32 vcc, v147, v125
	s_nop 1
	v_cndmask_b32_e32 v71, v226, v71, vcc
	v_cmp_gt_i32_e32 vcc, v148, v124
	s_nop 1
	v_cndmask_b32_e32 v64, v64, v82, vcc
	v_cmp_le_i32_e32 vcc, v149, v124
	s_nop 1
	v_cndmask_b32_e32 v65, v226, v65, vcc
	v_cmp_le_i32_e32 vcc, v150, v124
	s_nop 1
	v_cndmask_b32_e32 v66, v226, v66, vcc
	v_cmp_le_i32_e32 vcc, v151, v124
	s_nop 1
	v_cndmask_b32_e32 v67, v226, v67, vcc
	v_cmp_gt_i32_e32 vcc, v148, v125
	s_nop 1
	v_cndmask_b32_e32 v60, v60, v82, vcc
	v_cmp_le_i32_e32 vcc, v149, v125
	s_nop 1
	v_cndmask_b32_e32 v61, v226, v61, vcc
	v_cmp_le_i32_e32 vcc, v150, v125
	s_nop 1
	v_cndmask_b32_e32 v62, v226, v62, vcc
	v_cmp_le_i32_e32 vcc, v151, v125
	s_nop 1
	v_cndmask_b32_e32 v63, v226, v63, vcc
	v_cmp_gt_i32_e32 vcc, v152, v124
	s_nop 1
	v_cndmask_b32_e32 v56, v56, v82, vcc
	v_cmp_le_i32_e32 vcc, v153, v124
	s_nop 1
	v_cndmask_b32_e32 v57, v226, v57, vcc
	v_cmp_le_i32_e32 vcc, v154, v124
	s_nop 1
	v_cndmask_b32_e32 v58, v226, v58, vcc
	v_cmp_le_i32_e32 vcc, v155, v124
	s_nop 1
	v_cndmask_b32_e32 v59, v226, v59, vcc
	v_cmp_gt_i32_e32 vcc, v152, v125
	s_nop 1
	v_cndmask_b32_e32 v52, v52, v82, vcc
	v_cmp_le_i32_e32 vcc, v153, v125
	s_nop 1
	v_cndmask_b32_e32 v53, v226, v53, vcc
	v_cmp_le_i32_e32 vcc, v154, v125
	s_nop 1
	v_cndmask_b32_e32 v54, v226, v54, vcc
	v_cmp_le_i32_e32 vcc, v155, v125
	s_nop 1
	v_cndmask_b32_e32 v55, v226, v55, vcc
; #define LAS __attribute__((address_space(3)))
; __device__ __forceinline__ unsigned pk2(float lo, float hi) { const f32x2_t v = {lo, hi}; const bf16x2_t b = __builtin_convertvector(v, bf16x2_t); return __builtin_bit_cast(unsigned, b); }
; template <bool MOBA>
; __device__ __forceinline__ void attn_unit(unsigned char* lds, LAS unsigned char* lds3, const Params& p, int b, int h, int qb) {
;     ...
;             {
; #pragma unroll
;             for (int jb = 0; jb < 2; ++jb) { float ls = 0.f;
; #pragma unroll
;                 for (int kb = 0; kb < 4; ++kb)
; #pragma unroll
;                     for (int r = 0; r < 4; ++r) { const float e = __builtin_amdgcn_exp2f(s[kb][jb][r]); s[kb][jb][r] = e; ls += e; }
;                 lrow[jb] += ls; }
;             { u32x2 vlo[2][4], vhi[2][4];
; #pragma unroll
;             for (int ks2 = 0; ks2 < 2; ++ks2)
; #pragma unroll
;                 for (int db = 0; db < 4; ++db) { const int d = 32 * (db >> 1) + 8 * (fr >> 2) + 4 * (db & 1) + (fr & 3);        const int kx = (32 * ks2 + 4 * fq) ^ (((d >> 3) & 7) << 3);
;                     vlo[ks2][db] = *(const LAS u32x2*)(Vt + slot * 4608 + d * 72 + kx); vhi[ks2][db] = *(const LAS u32x2*)(Vt + slot * 4608 + d * 72 + (kx ^ 16)); }
;             bf16x8 pf[2][2];
; #pragma unroll
;             for (int ks2 = 0; ks2 < 2; ++ks2)
; #pragma unroll
;                 for (int jb = 0; jb < 2; ++jb) { const f32x4 a = s[2 * ks2][jb], c = s[2 * ks2 + 1][jb]; u32x4 pw; pw.x = pk2(a[0], a[1]); pw.y = pk2(a[2], a[3]); pw.z = pk2(c[0], c[1]); pw.w = pk2(c[2], c[3]); pf[ks2][jb] = __builtin_bit_cast(bf16x8, pw); }
;             __builtin_amdgcn_sched_barrier(0);
; #pragma unroll
;             for (int ks2 = 0; ks2 < 2; ++ks2)
; #pragma unroll
;                 for (int db = 0; db < 4; ++db) { u32x4 vv; vv.x = vlo[ks2][db].x; vv.y = vlo[ks2][db].y; vv.z = vhi[ks2][db].x; vv.w = vhi[ks2][db].y; const bf16x8 vf = __builtin_bit_cast(bf16x8, vv);
;                     o[db][0] = __builtin_amdgcn_mfma_f32_16x16x32_bf16(vf, pf[ks2][0], o[db][0], 0, 0, 0); o[db][1] = __builtin_amdgcn_mfma_f32_16x16x32_bf16(vf, pf[ks2][1], o[db][1], 0, 0, 0); }
.LBB0_438:
	v_exp_f32_e32 v83, v72
	v_exp_f32_e32 v82, v76
	v_exp_f32_e32 v97, v73
	v_exp_f32_e32 v96, v77
	v_exp_f32_e32 v99, v2
	v_exp_f32_e32 v98, v74
	v_exp_f32_e32 v3, v3
	v_exp_f32_e32 v2, v75
	v_exp_f32_e32 v101, v80
	v_exp_f32_e32 v181, v56
	v_exp_f32_e32 v183, v57
	v_exp_f32_e32 v100, v68
	v_add_f32_e32 v56, 0, v82
	v_add_f32_e32 v57, 0, v83
	v_exp_f32_e32 v103, v81
	v_add_f32_e32 v56, v96, v56
	v_add_f32_e32 v57, v97, v57
	v_exp_f32_e32 v102, v69
	v_exp_f32_e32 v111, v78
	v_add_f32_e32 v56, v98, v56
	v_add_f32_e32 v57, v99, v57
	v_exp_f32_e32 v110, v70
	v_exp_f32_e32 v113, v79
	v_add_f32_e32 v56, v2, v56
	v_add_f32_e32 v57, v3, v57
	v_exp_f32_e32 v112, v71
	v_exp_f32_e32 v115, v64
	v_add_f32_e32 v56, v100, v56
	v_add_f32_e32 v57, v101, v57
	v_exp_f32_e32 v114, v60
	v_exp_f32_e32 v131, v65
	v_exp_f32_e32 v130, v61
	v_exp_f32_e32 v180, v52
	v_exp_f32_e32 v182, v53
	v_add_f32_e32 v52, v102, v56
	v_add_f32_e32 v53, v103, v57
	v_exp_f32_e32 v171, v66
	v_exp_f32_e32 v170, v62
	v_add_f32_e32 v52, v110, v52
	v_add_f32_e32 v53, v111, v53
	v_exp_f32_e32 v173, v67
	v_exp_f32_e32 v172, v63
	v_add_f32_e32 v52, v112, v52
	v_add_f32_e32 v53, v113, v53
	v_exp_f32_e32 v185, v58
	v_add_f32_e32 v52, v114, v52
	v_add_f32_e32 v53, v115, v53
	v_exp_f32_e32 v184, v54
	v_add_f32_e32 v52, v130, v52
	v_add_f32_e32 v53, v131, v53
	v_exp_f32_e32 v187, v59
	v_add_f32_e32 v52, v170, v52
	v_add_f32_e32 v53, v171, v53
	v_exp_f32_e32 v186, v55
	v_add_f32_e32 v52, v172, v52
	v_add_f32_e32 v53, v173, v53
	v_add_u32_e32 v1, 0, v157
	v_add_f32_e32 v52, v180, v52
	v_add_f32_e32 v53, v181, v53
	v_lshlrev_b32_e32 v54, 1, v158
	v_add_f32_e32 v52, v182, v52
	v_add_f32_e32 v53, v183, v53
	v_add_u32_e32 v68, 0, v159
	v_add_f32_e32 v52, v184, v52
	v_add_f32_e32 v53, v185, v53
	v_add_u32_e32 v76, 0, v161
	v_add_f32_e32 v52, v186, v52
	v_add_f32_e32 v53, v187, v53
	v_lshlrev_b32_e32 v60, 1, v160
	v_add_f32_e32 v126, 0, v52
	v_add_f32_e32 v127, 0, v53
	v_lshlrev_b32_e32 v52, 1, v156
	v_lshlrev_b32_e32 v62, 1, v162
	v_add_u32_e32 v77, 0, v163
	v_lshlrev_b32_e32 v69, 1, v164
	v_lshlrev_b32_e32 v71, 1, v165
	v_add_u32_e32 v53, v1, v52
	v_add_u32_e32 v55, v1, v54
	v_add_u32_e32 v56, v68, v52
	v_add_u32_e32 v58, v68, v54
	v_add_u32_e32 v61, v76, v60
	v_add_u32_e32 v63, v76, v62
	v_add_u32_e32 v64, v77, v60
	v_add_u32_e32 v66, v77, v62
	v_add_u32_e32 v70, v1, v69
	v_add_u32_e32 v1, v1, v71
	v_add_u32_e32 v72, v68, v69
	v_add_u32_e32 v74, v68, v71
	ds_read_b64 v[52:53], v53 offset:36864
	ds_read_b64 v[54:55], v55 offset:36864
	ds_read_b64 v[56:57], v56 offset:36864
	ds_read_b64 v[58:59], v58 offset:36864
	ds_read_b64 v[60:61], v61 offset:36864
	ds_read_b64 v[62:63], v63 offset:36864
	ds_read_b64 v[64:65], v64 offset:36864
	ds_read_b64 v[66:67], v66 offset:36864
	ds_read_b64 v[68:69], v70 offset:36864
	ds_read_b64 v[70:71], v1 offset:36864
	ds_read_b64 v[72:73], v72 offset:36864
	ds_read_b64 v[74:75], v74 offset:36864
	v_lshlrev_b32_e32 v1, 1, v166
	v_add_u32_e32 v78, v76, v1
	v_lshlrev_b32_e32 v79, 1, v167
	v_add_u32_e32 v76, v76, v79
	v_add_u32_e32 v1, v77, v1
	v_add_u32_e32 v77, v77, v79
	ds_read_b64 v[88:89], v78 offset:36864
	ds_read_b64 v[90:91], v76 offset:36864
	ds_read_b64 v[92:93], v1 offset:36864
	ds_read_b64 v[94:95], v77 offset:36864
	v_cvt_pk_bf16_f32 v76, v83, v97
	v_cvt_pk_bf16_f32 v77, v99, v3
	v_cvt_pk_bf16_f32 v78, v101, v103
	v_cvt_pk_bf16_f32 v79, v111, v113
	v_cvt_pk_bf16_f32 v80, v82, v96
	v_cvt_pk_bf16_f32 v81, v98, v2
	v_cvt_pk_bf16_f32 v82, v100, v102
	v_cvt_pk_bf16_f32 v83, v110, v112
	v_cvt_pk_bf16_f32 v96, v115, v131
	v_cvt_pk_bf16_f32 v97, v171, v173
	v_cvt_pk_bf16_f32 v98, v181, v183
	v_cvt_pk_bf16_f32 v99, v185, v187
	v_cvt_pk_bf16_f32 v100, v114, v130
	v_cvt_pk_bf16_f32 v101, v170, v172
	v_cvt_pk_bf16_f32 v102, v180, v182
	v_cvt_pk_bf16_f32 v103, v184, v186
	s_waitcnt lgkmcnt(14)
	v_mfma_f32_16x16x32_bf16 v[110:113], v[52:55], v[76:79], 0
	v_mfma_f32_16x16x32_bf16 v[52:55], v[52:55], v[80:83], 0
	s_waitcnt lgkmcnt(12)
	v_mfma_f32_16x16x32_bf16 v[170:173], v[56:59], v[76:79], 0
	v_mfma_f32_16x16x32_bf16 v[56:59], v[56:59], v[80:83], 0
	s_waitcnt lgkmcnt(10)
	v_mfma_f32_16x16x32_bf16 v[180:183], v[60:63], v[76:79], 0
	v_mfma_f32_16x16x32_bf16 v[184:187], v[60:63], v[80:83], 0
	s_waitcnt lgkmcnt(8)
	v_mfma_f32_16x16x32_bf16 v[188:191], v[64:67], v[76:79], 0
	v_mfma_f32_16x16x32_bf16 v[192:195], v[64:67], v[80:83], 0
	s_waitcnt lgkmcnt(6)
	v_mfma_f32_16x16x32_bf16 v[80:83], v[68:71], v[96:99], v[110:113]
	v_mfma_f32_16x16x32_bf16 v[64:67], v[68:71], v[100:103], v[52:55]
	s_waitcnt lgkmcnt(4)
	v_mfma_f32_16x16x32_bf16 v[76:79], v[72:75], v[96:99], v[170:173]
	v_mfma_f32_16x16x32_bf16 v[60:63], v[72:75], v[100:103], v[56:59]
	s_waitcnt lgkmcnt(2)
	v_mfma_f32_16x16x32_bf16 v[72:75], v[88:91], v[96:99], v[180:183]
	v_mfma_f32_16x16x32_bf16 v[56:59], v[88:91], v[100:103], v[184:187]
	s_waitcnt lgkmcnt(0)
	v_mfma_f32_16x16x32_bf16 v[68:71], v[92:95], v[96:99], v[188:191]
	v_mfma_f32_16x16x32_bf16 v[52:55], v[92:95], v[100:103], v[192:195]
	s_branch .LBB0_440

; #define LAS __attribute__((address_space(3)))
; template <bool MOBA>
; __device__ __forceinline__ void attn_unit(unsigned char* lds, LAS unsigned char* lds3, const Params& p, int b, int h, int qb) {
;     ...
;             f32x4 s[4][2];
;             bool band = false;
;             if (!MOBA) {
;                 const float f0 = fq2[0] - mref[0], f1 = fq2[1] - mref[1];
; #pragma unroll
;                 for (int kb = 0; kb < 4; ++kb) { const f32x4 fk = *(const LAS f32x4*)(Fs + 64 * t + 16 * kb + 4 * fq); s[kb][0] = f0 - fk; s[kb][1] = f1 - fk; }
;             } else {
;                 band = (t >> 2) >= qb - 1;
;                 const float cc = band ? 0.f : c31;
;                 const float c0 = (qv[0] ? cc : NEGBIG) - mrc[0], c1 = (qv[1] ? cc : NEGBIG) - mrc[1];
; #pragma unroll
;                 for (int kb = 0; kb < 4; ++kb) { s[kb][0] = (f32x4){c0, c0, c0, c0}; s[kb][1] = (f32x4){c1, c1, c1, c1}; }
;             }
;             { bf16x8 kf[4][2];
; #pragma unroll
;             for (int kb = 0; kb < 4; ++kb)
; #pragma unroll
;                 for (int ks = 0; ks < 2; ++ks) kf[kb][ks] = *(const LAS bf16x8*)(Ks + slot * 4608 + (16 * kb + fr) * 72 + 32 * ks + 8 * fq);
;             __builtin_amdgcn_sched_barrier(0);
; #pragma unroll
;             for (int kb = 0; kb < 4; ++kb)
; #pragma unroll
;                 for (int ks = 0; ks < 2; ++ks) {
;                     s[kb][0] = __builtin_amdgcn_mfma_f32_16x16x32_bf16(kf[kb][ks], qf[0][ks], s[kb][0], 0, 0, 0); s[kb][1] = __builtin_amdgcn_mfma_f32_16x16x32_bf16(kf[kb][ks], qf[1][ks], s[kb][1], 0, 0, 0); }
;             __builtin_amdgcn_sched_barrier(0); }
;             if (MOBA && band) {
;                 asm volatile("" ::: "memory");
; #pragma unroll
;                 for (int kb = 0; kb < 4; ++kb)
; #pragma unroll
;                     for (int jb = 0; jb < 2; ++jb)
; #pragma unroll
;                         for (int r = 0; r < 4; ++r) { int d = (256 * qb + qpl[jb]) - (64 * t + 16 * kb + 4 * fq + r); d = d < 0 ? 0 : (d > 127 ? 127 : d); s[kb][jb][r] += tbl[d]; }
.LBB0_456:
	v_sub_f32_e32 v88, v85, v122
	s_waitcnt lgkmcnt(0)
	v_sub_f32_e32 v110, v86, v123
	ds_read_b128 v[92:95], v84 offset:9216
	ds_read_b128 v[96:99], v84 offset:9280
	ds_read_b128 v[100:103], v84 offset:11520
	ds_read_b128 v[170:173], v84 offset:11584
	ds_read_b128 v[180:183], v84 offset:13824
	ds_read_b128 v[184:187], v84 offset:13888
	ds_read_b128 v[188:191], v84 offset:16128
	ds_read_b128 v[84:87], v84 offset:16192
	v_mov_b32_e32 v89, v88
	v_mov_b32_e32 v90, v88
	v_mov_b32_e32 v91, v88
	v_mov_b32_e32 v111, v110
	v_mov_b32_e32 v112, v110
	v_mov_b32_e32 v113, v110
	s_waitcnt lgkmcnt(7)
	v_mfma_f32_16x16x32_bf16 v[192:195], v[92:95], v[8:11], v[88:91]
	s_lshl_b32 s5, s4, 6
	s_add_i32 s4, 0, 0x13000
	s_cmp_lg_u32 s14, s21
	v_mfma_f32_16x16x32_bf16 v[92:95], v[92:95], v[16:19], v[110:113]
	s_waitcnt lgkmcnt(6)
	v_mfma_f32_16x16x32_bf16 v[192:195], v[96:99], v[4:7], v[192:195]
	v_mfma_f32_16x16x32_bf16 v[196:199], v[96:99], v[12:15], v[92:95]
	s_waitcnt lgkmcnt(5)
	v_mfma_f32_16x16x32_bf16 v[92:95], v[100:103], v[8:11], v[88:91]
	v_mfma_f32_16x16x32_bf16 v[96:99], v[100:103], v[16:19], v[110:113]
	s_waitcnt lgkmcnt(4)
	v_mfma_f32_16x16x32_bf16 v[200:203], v[170:173], v[4:7], v[92:95]
	v_mfma_f32_16x16x32_bf16 v[100:103], v[170:173], v[12:15], v[96:99]
	s_waitcnt lgkmcnt(3)
	v_mfma_f32_16x16x32_bf16 v[92:95], v[180:183], v[8:11], v[88:91]
	v_mfma_f32_16x16x32_bf16 v[170:173], v[180:183], v[16:19], v[110:113]
	s_waitcnt lgkmcnt(1)
	v_mfma_f32_16x16x32_bf16 v[88:91], v[188:191], v[8:11], v[88:91]
	v_mfma_f32_16x16x32_bf16 v[110:113], v[188:191], v[16:19], v[110:113]
	v_mfma_f32_16x16x32_bf16 v[96:99], v[184:187], v[4:7], v[92:95]
	v_mfma_f32_16x16x32_bf16 v[92:95], v[184:187], v[12:15], v[170:173]
	s_waitcnt lgkmcnt(0)
	v_mfma_f32_16x16x32_bf16 v[88:91], v[84:87], v[4:7], v[88:91]
	v_mfma_f32_16x16x32_bf16 v[84:87], v[84:87], v[12:15], v[110:113]
	v_subrev_u32_e32 v1, s5, v139
	v_add_u32_e32 v1, s42, v1
	v_add_u32_e32 v3, v124, v1
	v_add_u32_e32 v1, v125, v1
	v_med3_i32 v2, v3, 0, v227
	v_med3_i32 v112, v1, 0, v227
	v_lshl_add_u32 v2, v2, 2, s4
	v_lshl_add_u32 v112, v112, 2, s4
	ds_read_b32 v110, v2
	ds_read_b32 v114, v112
	v_add_u32_e32 v112, -1, v1
	v_med3_i32 v112, v112, 0, v227
	v_lshl_add_u32 v112, v112, 2, s4
	ds_read_b32 v115, v112
	v_add_u32_e32 v112, -2, v1
	v_add_u32_e32 v1, -3, v1
	v_med3_i32 v1, v1, 0, v227
	v_lshl_add_u32 v1, v1, 2, s4
	ds_read_b32 v113, v1
	v_subrev_u32_e32 v1, s5, v128
	v_add_u32_e32 v129, v124, v1
	v_add_u32_e32 v1, v125, v1
	v_add_u32_e32 v2, -1, v3
	v_add_u32_e32 v171, -1, v1
	v_med3_i32 v2, v2, 0, v227
	v_med3_i32 v112, v112, 0, v227
	v_med3_i32 v170, v1, 0, v227
	v_med3_i32 v171, v171, 0, v227
	v_lshl_add_u32 v2, v2, 2, s4
	v_lshl_add_u32 v112, v112, 2, s4
	v_lshl_add_u32 v170, v170, 2, s4
	v_lshl_add_u32 v171, v171, 2, s4
	v_add_u32_e32 v172, -2, v1
	v_add_u32_e32 v1, -3, v1
	ds_read_b32 v111, v2
	ds_read_b32 v112, v112
	ds_read_b32 v170, v170
	ds_read_b32 v171, v171
	v_med3_i32 v172, v172, 0, v227
	v_med3_i32 v1, v1, 0, v227
	v_lshl_add_u32 v172, v172, 2, s4
	v_lshl_add_u32 v1, v1, 2, s4
	ds_read_b32 v172, v172
	ds_read_b32 v173, v1
	v_subrev_u32_e32 v1, s5, v169
	v_add_u32_e32 v169, v124, v1
	s_waitcnt lgkmcnt(2)
	v_add_f32_e32 v100, v100, v170
	v_add_f32_e32 v101, v101, v171
	v_add_u32_e32 v171, -1, v169
	v_med3_i32 v170, v169, 0, v227
	v_med3_i32 v171, v171, 0, v227
	v_add_u32_e32 v2, -2, v3
	s_waitcnt lgkmcnt(0)
	v_add_f32_e32 v102, v102, v172
	v_add_f32_e32 v103, v103, v173
	v_lshl_add_u32 v170, v170, 2, s4
	v_lshl_add_u32 v171, v171, 2, s4
	v_add_u32_e32 v172, -2, v169
	v_add_u32_e32 v169, -3, v169
	v_med3_i32 v2, v2, 0, v227
	v_med3_i32 v128, v129, 0, v227
	ds_read_b32 v170, v170
	ds_read_b32 v171, v171
	v_med3_i32 v169, v169, 0, v227
	v_lshl_add_u32 v2, v2, 2, s4
	v_lshl_add_u32 v128, v128, 2, s4
	v_lshl_add_u32 v169, v169, 2, s4
	ds_read_b32 v2, v2
	ds_read_b32 v130, v128
	ds_read_b32 v173, v169
	v_add_u32_e32 v128, -1, v129
	v_add_u32_e32 v1, v125, v1
	v_med3_i32 v128, v128, 0, v227
	v_med3_i32 v172, v172, 0, v227
	v_med3_i32 v169, v1, 0, v227
	v_lshl_add_u32 v128, v128, 2, s4
	v_lshl_add_u32 v172, v172, 2, s4
	v_lshl_add_u32 v169, v169, 2, s4
	ds_read_b32 v131, v128
	ds_read_b32 v172, v172
	s_waitcnt lgkmcnt(5)
	v_add_f32_e32 v96, v96, v170
	v_add_f32_e32 v97, v97, v171
	ds_read_b32 v170, v169
	v_add_u32_e32 v169, -1, v1
	v_med3_i32 v169, v169, 0, v227
	v_lshl_add_u32 v169, v169, 2, s4
	ds_read_b32 v171, v169
	v_add_u32_e32 v169, -2, v1
	v_add_u32_e32 v1, -3, v1
	v_med3_i32 v1, v1, 0, v227
	v_lshl_add_u32 v1, v1, 2, s4
	s_waitcnt lgkmcnt(2)
	v_add_f32_e32 v98, v98, v172
	v_add_f32_e32 v99, v99, v173
	v_med3_i32 v169, v169, 0, v227
	ds_read_b32 v173, v1
	v_subrev_u32_e32 v1, s5, v105
	v_lshl_add_u32 v169, v169, 2, s4
	v_add_u32_e32 v105, v124, v1
	ds_read_b32 v172, v169
	v_med3_i32 v169, v105, 0, v227
	v_lshl_add_u32 v169, v169, 2, s4
	s_waitcnt lgkmcnt(2)
	v_add_f32_e32 v92, v92, v170
	v_add_f32_e32 v93, v93, v171
	ds_read_b32 v170, v169
	v_add_u32_e32 v169, -1, v105
	v_med3_i32 v169, v169, 0, v227
	v_lshl_add_u32 v169, v169, 2, s4
	v_add_u32_e32 v3, -3, v3
	ds_read_b32 v171, v169
	v_add_u32_e32 v169, -2, v105
	v_add_u32_e32 v105, -3, v105
	v_med3_i32 v3, v3, 0, v227
	v_med3_i32 v105, v105, 0, v227
	v_lshl_add_u32 v3, v3, 2, s4
	v_lshl_add_u32 v105, v105, 2, s4
	ds_read_b32 v3, v3
	s_waitcnt lgkmcnt(3)
	v_add_f32_e32 v94, v94, v172
	v_add_f32_e32 v95, v95, v173
	ds_read_b32 v173, v105
	v_add_u32_e32 v128, -2, v129
	v_add_u32_e32 v1, v125, v1
	v_med3_i32 v128, v128, 0, v227
	v_med3_i32 v169, v169, 0, v227
	v_med3_i32 v105, v1, 0, v227
	v_lshl_add_u32 v128, v128, 2, s4
	v_lshl_add_u32 v169, v169, 2, s4
	v_lshl_add_u32 v105, v105, 2, s4
	ds_read_b32 v128, v128
	ds_read_b32 v172, v169
	v_add_u32_e32 v129, -3, v129
	s_waitcnt lgkmcnt(4)
	v_add_f32_e32 v88, v88, v170
	v_add_f32_e32 v89, v89, v171
	ds_read_b32 v170, v105
	v_add_u32_e32 v105, -1, v1
	v_med3_i32 v129, v129, 0, v227
	v_med3_i32 v105, v105, 0, v227
	v_lshl_add_u32 v129, v129, 2, s4
	v_lshl_add_u32 v105, v105, 2, s4
	ds_read_b32 v129, v129
	ds_read_b32 v171, v105
	v_add_u32_e32 v105, -2, v1
	v_add_u32_e32 v1, -3, v1
	v_med3_i32 v105, v105, 0, v227
	v_med3_i32 v1, v1, 0, v227
	v_lshl_add_u32 v105, v105, 2, s4
	v_lshl_add_u32 v1, v1, 2, s4
	s_waitcnt lgkmcnt(3)
	v_add_f32_e32 v90, v90, v172
	v_add_f32_e32 v91, v91, v173
	ds_read_b32 v172, v105
	ds_read_b32 v173, v1
	v_add_f32_e32 v2, v194, v2
	v_add_f32_e32 v3, v195, v3
	v_add_f32_e32 v110, v192, v110
	v_add_f32_e32 v111, v193, v111
	v_add_f32_e32 v112, v198, v112
	v_add_f32_e32 v113, v199, v113
	v_add_f32_e32 v114, v196, v114
	v_add_f32_e32 v115, v197, v115
	s_waitcnt lgkmcnt(3)
	v_add_f32_e32 v128, v202, v128
	v_add_f32_e32 v129, v203, v129
	v_add_f32_e32 v130, v200, v130
	v_add_f32_e32 v131, v201, v131
	s_waitcnt lgkmcnt(0)
	v_add_f32_e32 v86, v86, v172
	v_add_f32_e32 v87, v87, v173
	v_add_f32_e32 v84, v84, v170
	v_add_f32_e32 v85, v85, v171
	s_cbranch_scc1 .LBB0_458
; template <bool MOBA>
; __device__ __forceinline__ void attn_unit(unsigned char* lds, LAS unsigned char* lds3, const Params& p, int b, int h, int qb) {
;     ...
;             if (diag) {
;                 asm volatile("" ::: "memory");
; #pragma unroll
;                 for (int kb = 0; kb < 4; ++kb)
; #pragma unroll
;                     for (int jb = 0; jb < 2; ++jb)
; #pragma unroll
;                         for (int r = 0; r < 4; ++r) { if ((64 * tl + 16 * kb + 4 * fq + r) > (MOBA ? qpl[jb] : qloc + 16 * jb)) s[kb][jb][r] = NEGBIG; }
;             }
	v_mov_b32_e32 v170, s93
	v_cmp_gt_i32_e32 vcc, v141, v124
	s_nop 1
	v_cndmask_b32_e32 v1, v110, v170, vcc
	v_cmp_lt_i32_e32 vcc, v141, v124
	s_nop 1
	v_cndmask_b32_e32 v110, v1, v110, vcc
	v_cndmask_b32_e32 v111, v226, v111, vcc
	v_cmp_le_i32_e32 vcc, v142, v124
	s_nop 1
	v_cndmask_b32_e32 v2, v226, v2, vcc
	v_cmp_le_i32_e32 vcc, v143, v124
	s_nop 1
	v_cndmask_b32_e32 v3, v226, v3, vcc
	v_cmp_gt_i32_e32 vcc, v141, v125
	s_nop 1
	v_cndmask_b32_e32 v1, v114, v170, vcc
	v_cmp_lt_i32_e32 vcc, v141, v125
	s_nop 1
	v_cndmask_b32_e32 v114, v1, v114, vcc
	v_cndmask_b32_e32 v115, v226, v115, vcc
	v_cmp_le_i32_e32 vcc, v142, v125
	s_nop 1
	v_cndmask_b32_e32 v112, v226, v112, vcc
	v_cmp_le_i32_e32 vcc, v143, v125
	s_nop 1
	v_cndmask_b32_e32 v113, v226, v113, vcc
	v_cmp_gt_i32_e32 vcc, v144, v124
	s_nop 1
	v_cndmask_b32_e32 v130, v130, v170, vcc
	v_cmp_le_i32_e32 vcc, v145, v124
	s_nop 1
	v_cndmask_b32_e32 v131, v226, v131, vcc
	v_cmp_le_i32_e32 vcc, v146, v124
	s_nop 1
	v_cndmask_b32_e32 v128, v226, v128, vcc
	v_cmp_le_i32_e32 vcc, v147, v124
	s_nop 1
	v_cndmask_b32_e32 v129, v226, v129, vcc
	v_cmp_gt_i32_e32 vcc, v144, v125
	s_nop 1
	v_cndmask_b32_e32 v100, v100, v170, vcc
	v_cmp_le_i32_e32 vcc, v145, v125
	s_nop 1
	v_cndmask_b32_e32 v101, v226, v101, vcc
	v_cmp_le_i32_e32 vcc, v146, v125
	s_nop 1
	v_cndmask_b32_e32 v102, v226, v102, vcc
	v_cmp_le_i32_e32 vcc, v147, v125
	s_nop 1
	v_cndmask_b32_e32 v103, v226, v103, vcc
	v_cmp_gt_i32_e32 vcc, v148, v124
	s_nop 1
	v_cndmask_b32_e32 v96, v96, v170, vcc
	v_cmp_le_i32_e32 vcc, v149, v124
	s_nop 1
	v_cndmask_b32_e32 v97, v226, v97, vcc
	v_cmp_le_i32_e32 vcc, v150, v124
	s_nop 1
	v_cndmask_b32_e32 v98, v226, v98, vcc
	v_cmp_le_i32_e32 vcc, v151, v124
	s_nop 1
	v_cndmask_b32_e32 v99, v226, v99, vcc
	v_cmp_gt_i32_e32 vcc, v148, v125
	s_nop 1
	v_cndmask_b32_e32 v92, v92, v170, vcc
	v_cmp_le_i32_e32 vcc, v149, v125
	s_nop 1
	v_cndmask_b32_e32 v93, v226, v93, vcc
	v_cmp_le_i32_e32 vcc, v150, v125
	s_nop 1
	v_cndmask_b32_e32 v94, v226, v94, vcc
	v_cmp_le_i32_e32 vcc, v151, v125
	s_nop 1
	v_cndmask_b32_e32 v95, v226, v95, vcc
	v_cmp_gt_i32_e32 vcc, v152, v124
	s_nop 1
	v_cndmask_b32_e32 v88, v88, v170, vcc
	v_cmp_le_i32_e32 vcc, v153, v124
	s_nop 1
	v_cndmask_b32_e32 v89, v226, v89, vcc
	v_cmp_le_i32_e32 vcc, v154, v124
	s_nop 1
	v_cndmask_b32_e32 v90, v226, v90, vcc
	v_cmp_le_i32_e32 vcc, v155, v124
	s_nop 1
	v_cndmask_b32_e32 v91, v226, v91, vcc
	v_cmp_gt_i32_e32 vcc, v152, v125
	s_nop 1
	v_cndmask_b32_e32 v84, v84, v170, vcc
	v_cmp_le_i32_e32 vcc, v153, v125
	s_nop 1
	v_cndmask_b32_e32 v85, v226, v85, vcc
	v_cmp_le_i32_e32 vcc, v154, v125
	s_nop 1
	v_cndmask_b32_e32 v86, v226, v86, vcc
	v_cmp_le_i32_e32 vcc, v155, v125
	s_nop 1
	v_cndmask_b32_e32 v87, v226, v87, vcc
; #define LAS __attribute__((address_space(3)))
; __device__ __forceinline__ unsigned pk2(float lo, float hi) { const f32x2_t v = {lo, hi}; const bf16x2_t b = __builtin_convertvector(v, bf16x2_t); return __builtin_bit_cast(unsigned, b); }
; template <bool MOBA>
; __device__ __forceinline__ void attn_unit(unsigned char* lds, LAS unsigned char* lds3, const Params& p, int b, int h, int qb) {
;     ...
;             {
; #pragma unroll
;             for (int jb = 0; jb < 2; ++jb) { float ls = 0.f;
; #pragma unroll
;                 for (int kb = 0; kb < 4; ++kb)
; #pragma unroll
;                     for (int r = 0; r < 4; ++r) { const float e = __builtin_amdgcn_exp2f(s[kb][jb][r]); s[kb][jb][r] = e; ls += e; }
;                 lrow[jb] += ls; }
;             { u32x2 vlo[2][4], vhi[2][4];
; #pragma unroll
;             for (int ks2 = 0; ks2 < 2; ++ks2)
; #pragma unroll
;                 for (int db = 0; db < 4; ++db) { const int d = 32 * (db >> 1) + 8 * (fr >> 2) + 4 * (db & 1) + (fr & 3);        const int kx = (32 * ks2 + 4 * fq) ^ (((d >> 3) & 7) << 3);
;                     vlo[ks2][db] = *(const LAS u32x2*)(Vt + slot * 4608 + d * 72 + kx); vhi[ks2][db] = *(const LAS u32x2*)(Vt + slot * 4608 + d * 72 + (kx ^ 16)); }
;             bf16x8 pf[2][2];
; #pragma unroll
;             for (int ks2 = 0; ks2 < 2; ++ks2)
; #pragma unroll
;                 for (int jb = 0; jb < 2; ++jb) { const f32x4 a = s[2 * ks2][jb], c = s[2 * ks2 + 1][jb]; u32x4 pw; pw.x = pk2(a[0], a[1]); pw.y = pk2(a[2], a[3]); pw.z = pk2(c[0], c[1]); pw.w = pk2(c[2], c[3]); pf[ks2][jb] = __builtin_bit_cast(bf16x8, pw); }
;             __builtin_amdgcn_sched_barrier(0);
; #pragma unroll
;             for (int ks2 = 0; ks2 < 2; ++ks2)
; #pragma unroll
;                 for (int db = 0; db < 4; ++db) { u32x4 vv; vv.x = vlo[ks2][db].x; vv.y = vlo[ks2][db].y; vv.z = vhi[ks2][db].x; vv.w = vhi[ks2][db].y; const bf16x8 vf = __builtin_bit_cast(bf16x8, vv);
;                     o[db][0] = __builtin_amdgcn_mfma_f32_16x16x32_bf16(vf, pf[ks2][0], o[db][0], 0, 0, 0); o[db][1] = __builtin_amdgcn_mfma_f32_16x16x32_bf16(vf, pf[ks2][1], o[db][1], 0, 0, 0); }
.LBB0_458:
	v_exp_f32_e32 v185, v110
	v_exp_f32_e32 v184, v114
	v_exp_f32_e32 v187, v111
	v_exp_f32_e32 v186, v115
	v_exp_f32_e32 v189, v2
	v_exp_f32_e32 v188, v112
	v_exp_f32_e32 v3, v3
	v_exp_f32_e32 v2, v113
	v_exp_f32_e32 v191, v130
	v_exp_f32_e32 v207, v88
	v_exp_f32_e32 v209, v89
	v_add_f32_e32 v88, 0, v184
	v_add_f32_e32 v89, 0, v185
	v_exp_f32_e32 v190, v100
	v_exp_f32_e32 v193, v131
	v_add_f32_e32 v88, v186, v88
	v_add_f32_e32 v89, v187, v89
	v_exp_f32_e32 v192, v101
	v_exp_f32_e32 v195, v128
	v_add_f32_e32 v88, v188, v88
	v_add_f32_e32 v89, v189, v89
	v_exp_f32_e32 v194, v102
	v_exp_f32_e32 v197, v129
	v_exp_f32_e32 v196, v103
	v_exp_f32_e32 v206, v84
	v_exp_f32_e32 v208, v85
	v_add_f32_e32 v84, v2, v88
	v_add_f32_e32 v85, v3, v89
	v_exp_f32_e32 v199, v96
	v_exp_f32_e32 v198, v92
	v_add_f32_e32 v84, v190, v84
	v_add_f32_e32 v85, v191, v85
	v_exp_f32_e32 v201, v97
	v_exp_f32_e32 v200, v93
	v_add_f32_e32 v84, v192, v84
	v_add_f32_e32 v85, v193, v85
	v_exp_f32_e32 v203, v98
	v_exp_f32_e32 v202, v94
	v_add_f32_e32 v84, v194, v84
	v_add_f32_e32 v85, v195, v85
	v_exp_f32_e32 v205, v99
	v_exp_f32_e32 v204, v95
	v_add_f32_e32 v84, v196, v84
	v_add_f32_e32 v85, v197, v85
	v_exp_f32_e32 v211, v90
	v_add_f32_e32 v84, v198, v84
	v_add_f32_e32 v85, v199, v85
	v_exp_f32_e32 v210, v86
	v_add_f32_e32 v84, v200, v84
	v_add_f32_e32 v85, v201, v85
	v_exp_f32_e32 v115, v91
	v_add_f32_e32 v84, v202, v84
	v_add_f32_e32 v85, v203, v85
	v_exp_f32_e32 v114, v87
	v_add_f32_e32 v84, v204, v84
	v_add_f32_e32 v85, v205, v85
	v_add_u32_e32 v1, 0, v157
	v_add_f32_e32 v84, v206, v84
	v_add_f32_e32 v85, v207, v85
	v_lshlrev_b32_e32 v86, 1, v158
	v_add_f32_e32 v84, v208, v84
	v_add_f32_e32 v85, v209, v85
	v_add_u32_e32 v100, 0, v159
	v_add_f32_e32 v84, v210, v84
	v_add_f32_e32 v85, v211, v85
	v_add_u32_e32 v105, 0, v161
	v_add_f32_e32 v84, v114, v84
	v_add_f32_e32 v85, v115, v85
	v_lshlrev_b32_e32 v92, 1, v160
	v_add_f32_e32 v126, v126, v84
	v_add_f32_e32 v127, v127, v85
	v_lshlrev_b32_e32 v84, 1, v156
	v_lshlrev_b32_e32 v94, 1, v162
	v_add_u32_e32 v128, 0, v163
	v_lshlrev_b32_e32 v101, 1, v164
	v_lshlrev_b32_e32 v103, 1, v165
	v_add_u32_e32 v85, v1, v84
	v_add_u32_e32 v87, v1, v86
	v_add_u32_e32 v88, v100, v84
	v_add_u32_e32 v90, v100, v86
	v_add_u32_e32 v93, v105, v92
	v_add_u32_e32 v95, v105, v94
	v_add_u32_e32 v96, v128, v92
	v_add_u32_e32 v98, v128, v94
	v_add_u32_e32 v102, v1, v101
	v_add_u32_e32 v1, v1, v103
	v_add_u32_e32 v110, v100, v101
	v_add_u32_e32 v112, v100, v103
	ds_read_b64 v[84:85], v85 offset:46080
	ds_read_b64 v[86:87], v87 offset:46080
	ds_read_b64 v[88:89], v88 offset:46080
	ds_read_b64 v[90:91], v90 offset:46080
	ds_read_b64 v[92:93], v93 offset:46080
	ds_read_b64 v[94:95], v95 offset:46080
	ds_read_b64 v[96:97], v96 offset:46080
	ds_read_b64 v[98:99], v98 offset:46080
	ds_read_b64 v[100:101], v102 offset:46080
	ds_read_b64 v[102:103], v1 offset:46080
	ds_read_b64 v[110:111], v110 offset:46080
	ds_read_b64 v[112:113], v112 offset:46080
	v_lshlrev_b32_e32 v1, 1, v166
	v_add_u32_e32 v129, v105, v1
	v_lshlrev_b32_e32 v130, 1, v167
	v_add_u32_e32 v105, v105, v130
	v_add_u32_e32 v1, v128, v1
	v_add_u32_e32 v169, v128, v130
	ds_read_b64 v[128:129], v129 offset:46080
	ds_read_b64 v[130:131], v105 offset:46080
	ds_read_b64 v[170:171], v1 offset:46080
	ds_read_b64 v[172:173], v169 offset:46080
	v_cvt_pk_bf16_f32 v180, v185, v187
	v_cvt_pk_bf16_f32 v181, v189, v3
	v_cvt_pk_bf16_f32 v182, v191, v193
	v_cvt_pk_bf16_f32 v183, v195, v197
	v_cvt_pk_bf16_f32 v184, v184, v186
	v_cvt_pk_bf16_f32 v185, v188, v2
	v_cvt_pk_bf16_f32 v186, v190, v192
	v_cvt_pk_bf16_f32 v187, v194, v196
	v_cvt_pk_bf16_f32 v188, v199, v201
	v_cvt_pk_bf16_f32 v189, v203, v205
	v_cvt_pk_bf16_f32 v190, v207, v209
	v_cvt_pk_bf16_f32 v191, v211, v115
	v_cvt_pk_bf16_f32 v192, v198, v200
	v_cvt_pk_bf16_f32 v193, v202, v204
	v_cvt_pk_bf16_f32 v194, v206, v208
	v_cvt_pk_bf16_f32 v195, v210, v114
	s_waitcnt lgkmcnt(14)
	v_mfma_f32_16x16x32_bf16 v[80:83], v[84:87], v[180:183], v[80:83]
	v_mfma_f32_16x16x32_bf16 v[64:67], v[84:87], v[184:187], v[64:67]
	s_waitcnt lgkmcnt(12)
	v_mfma_f32_16x16x32_bf16 v[76:79], v[88:91], v[180:183], v[76:79]
	v_mfma_f32_16x16x32_bf16 v[60:63], v[88:91], v[184:187], v[60:63]
	s_waitcnt lgkmcnt(10)
	v_mfma_f32_16x16x32_bf16 v[72:75], v[92:95], v[180:183], v[72:75]
	v_mfma_f32_16x16x32_bf16 v[56:59], v[92:95], v[184:187], v[56:59]
	s_waitcnt lgkmcnt(8)
	v_mfma_f32_16x16x32_bf16 v[68:71], v[96:99], v[180:183], v[68:71]
	v_mfma_f32_16x16x32_bf16 v[52:55], v[96:99], v[184:187], v[52:55]
	s_waitcnt lgkmcnt(6)
	v_mfma_f32_16x16x32_bf16 v[80:83], v[100:103], v[188:191], v[80:83]
	v_mfma_f32_16x16x32_bf16 v[64:67], v[100:103], v[192:195], v[64:67]
	s_waitcnt lgkmcnt(4)
	v_mfma_f32_16x16x32_bf16 v[76:79], v[110:113], v[188:191], v[76:79]
	v_mfma_f32_16x16x32_bf16 v[60:63], v[110:113], v[192:195], v[60:63]
	s_waitcnt lgkmcnt(2)
	v_mfma_f32_16x16x32_bf16 v[72:75], v[128:131], v[188:191], v[72:75]
	v_mfma_f32_16x16x32_bf16 v[56:59], v[128:131], v[192:195], v[56:59]
	s_waitcnt lgkmcnt(0)
	v_mfma_f32_16x16x32_bf16 v[68:71], v[170:173], v[188:191], v[68:71]
	v_mfma_f32_16x16x32_bf16 v[52:55], v[170:173], v[192:195], v[52:55]

; #define LAS __attribute__((address_space(3)))
; template <bool MOBA>
; __device__ __forceinline__ void attn_unit(unsigned char* lds, LAS unsigned char* lds3, const Params& p, int b, int h, int qb) {
;     ...
;             const bool diag = (tl == (w >> 1));
;             f32x4 s[4][2];
;             bool band = false;
;             if (!MOBA) {
;                 const float f0 = fq2[0] - mref[0], f1 = fq2[1] - mref[1];
; #pragma unroll
;                 for (int kb = 0; kb < 4; ++kb) { const f32x4 fk = *(const LAS f32x4*)(Fs + 64 * t + 16 * kb + 4 * fq); s[kb][0] = f0 - fk; s[kb][1] = f1 - fk; }
;             } else {
;                 band = (t >> 2) >= qb - 1;
;                 const float cc = band ? 0.f : c31;
;                 const float c0 = (qv[0] ? cc : NEGBIG) - mrc[0], c1 = (qv[1] ? cc : NEGBIG) - mrc[1];
; #pragma unroll
;                 for (int kb = 0; kb < 4; ++kb) { s[kb][0] = (f32x4){c0, c0, c0, c0}; s[kb][1] = (f32x4){c1, c1, c1, c1}; }
;             }
;             { bf16x8 kf[4][2];
; #pragma unroll
;             for (int kb = 0; kb < 4; ++kb)
; #pragma unroll
;                 for (int ks = 0; ks < 2; ++ks) kf[kb][ks] = *(const LAS bf16x8*)(Ks + slot * 4608 + (16 * kb + fr) * 72 + 32 * ks + 8 * fq);
;             __builtin_amdgcn_sched_barrier(0);
; #pragma unroll
;             for (int kb = 0; kb < 4; ++kb)
; #pragma unroll
;                 for (int ks = 0; ks < 2; ++ks) {
;                     s[kb][0] = __builtin_amdgcn_mfma_f32_16x16x32_bf16(kf[kb][ks], qf[0][ks], s[kb][0], 0, 0, 0); s[kb][1] = __builtin_amdgcn_mfma_f32_16x16x32_bf16(kf[kb][ks], qf[1][ks], s[kb][1], 0, 0, 0); }
;             __builtin_amdgcn_sched_barrier(0); }
.LBB0_478:
	s_and_b32 s18, s26, 2
	s_andn2_b64 vcc, exec, s[6:7]
	s_mul_i32 s6, s18, 0x2400
	v_add3_u32 v1, v138, s6, v140
	s_cbranch_vccnz .LBB0_485
	ds_read_b128 v[88:91], v1
	ds_read_b128 v[92:95], v1 offset:64
	ds_read_b128 v[104:107], v1 offset:2304
	ds_read_b128 v[170:173], v1 offset:2368
	ds_read_b128 v[180:183], v1 offset:4608
	ds_read_b128 v[184:187], v1 offset:4672
	ds_read_b128 v[188:191], v1 offset:6912
	ds_read_b128 v[192:195], v1 offset:6976
	s_ashr_i32 s4, s4, 2
	s_cmp_lt_i32 s4, s20
	s_cselect_b64 vcc, -1, 0
	v_cndmask_b32_e32 v2, 0, v133, vcc
	v_cndmask_b32_e64 v3, v226, v2, s[10:11]
	v_cndmask_b32_e64 v2, v226, v2, s[12:13]
	v_sub_f32_e32 v84, v3, v122
	s_waitcnt lgkmcnt(8)
	v_sub_f32_e32 v100, v2, v123
	v_mov_b32_e32 v85, v84
	v_mov_b32_e32 v86, v84
	v_mov_b32_e32 v87, v84
	v_mov_b32_e32 v101, v100
	v_mov_b32_e32 v102, v100
	v_mov_b32_e32 v103, v100
	s_waitcnt lgkmcnt(7)
	v_mfma_f32_16x16x32_bf16 v[96:99], v[88:91], v[8:11], v[84:87]
	v_mfma_f32_16x16x32_bf16 v[88:91], v[88:91], v[16:19], v[100:103]
	s_waitcnt lgkmcnt(6)
	v_mfma_f32_16x16x32_bf16 v[112:115], v[92:95], v[4:7], v[96:99]
	v_mfma_f32_16x16x32_bf16 v[96:99], v[92:95], v[12:15], v[88:91]
	s_waitcnt lgkmcnt(5)
	v_mfma_f32_16x16x32_bf16 v[88:91], v[104:107], v[8:11], v[84:87]
	v_mfma_f32_16x16x32_bf16 v[92:95], v[104:107], v[16:19], v[100:103]
	s_waitcnt lgkmcnt(4)
	v_mfma_f32_16x16x32_bf16 v[108:111], v[170:173], v[4:7], v[88:91]
	v_mfma_f32_16x16x32_bf16 v[92:95], v[170:173], v[12:15], v[92:95]
	s_waitcnt lgkmcnt(3)
	v_mfma_f32_16x16x32_bf16 v[88:91], v[180:183], v[8:11], v[84:87]
	v_mfma_f32_16x16x32_bf16 v[170:173], v[180:183], v[16:19], v[100:103]
	s_waitcnt lgkmcnt(2)
	v_mfma_f32_16x16x32_bf16 v[104:107], v[184:187], v[4:7], v[88:91]
	v_mfma_f32_16x16x32_bf16 v[88:91], v[184:187], v[12:15], v[170:173]
	s_waitcnt lgkmcnt(1)
	v_mfma_f32_16x16x32_bf16 v[84:87], v[188:191], v[8:11], v[84:87]
	v_mfma_f32_16x16x32_bf16 v[170:173], v[188:191], v[16:19], v[100:103]
	s_waitcnt lgkmcnt(0)
	v_mfma_f32_16x16x32_bf16 v[100:103], v[192:195], v[4:7], v[84:87]
	v_mfma_f32_16x16x32_bf16 v[84:87], v[192:195], v[12:15], v[170:173]
	s_and_b64 vcc, exec, vcc
	s_cbranch_vccnz .LBB0_481
; template <bool MOBA>
; __device__ __forceinline__ void attn_unit(unsigned char* lds, LAS unsigned char* lds3, const Params& p, int b, int h, int qb) {
;     ...
;             if (MOBA && band) {
;                 asm volatile("" ::: "memory");
; #pragma unroll
;                 for (int kb = 0; kb < 4; ++kb)
; #pragma unroll
;                     for (int jb = 0; jb < 2; ++jb)
; #pragma unroll
;                         for (int r = 0; r < 4; ++r) { int d = (256 * qb + qpl[jb]) - (64 * t + 16 * kb + 4 * fq + r); d = d < 0 ? 0 : (d > 127 ? 127 : d); s[kb][jb][r] += tbl[d]; }
;             }
	v_add3_u32 v169, v139, v124, s24
	v_subrev_u32_e32 v2, 64, v169
	v_add_u32_e32 v3, 0xffffffbf, v169
	v_med3_i32 v2, v2, 0, v227
	s_add_i32 s4, 0, 0x13000
	v_med3_i32 v3, v3, 0, v227
	v_lshl_add_u32 v2, v2, 2, s4
	v_lshl_add_u32 v3, v3, 2, s4
	ds_read_b32 v2, v2
	ds_read_b32 v3, v3
	v_add_u32_e32 v170, 0xffffffbe, v169
	v_add_u32_e32 v171, 0xffffffbd, v169
	v_med3_i32 v170, v170, 0, v227
	v_med3_i32 v171, v171, 0, v227
	v_lshl_add_u32 v170, v170, 2, s4
	v_lshl_add_u32 v171, v171, 2, s4
	ds_read_b32 v170, v170
	ds_read_b32 v171, v171
	v_add3_u32 v172, v139, v125, s24
	s_waitcnt lgkmcnt(2)
	v_add_f32_e32 v112, v112, v2
	v_add_f32_e32 v113, v113, v3
	v_subrev_u32_e32 v2, 64, v172
	v_add_u32_e32 v3, 0xffffffbf, v172
	v_med3_i32 v2, v2, 0, v227
	v_med3_i32 v3, v3, 0, v227
	v_lshl_add_u32 v2, v2, 2, s4
	v_lshl_add_u32 v3, v3, 2, s4
	s_waitcnt lgkmcnt(0)
	v_add_f32_e32 v114, v114, v170
	v_add_f32_e32 v115, v115, v171
	ds_read_b32 v2, v2
	ds_read_b32 v3, v3
	v_add_u32_e32 v170, 0xffffffbe, v172
	v_add_u32_e32 v171, 0xffffffbd, v172
	v_med3_i32 v170, v170, 0, v227
	v_med3_i32 v171, v171, 0, v227
	v_lshl_add_u32 v170, v170, 2, s4
	v_lshl_add_u32 v171, v171, 2, s4
	ds_read_b32 v170, v170
	ds_read_b32 v171, v171
	s_waitcnt lgkmcnt(2)
	v_add_f32_e32 v96, v96, v2
	v_add_f32_e32 v97, v97, v3
	v_add_u32_e32 v2, 0xffffffb0, v169
	v_add_u32_e32 v3, 0xffffffaf, v169
	v_med3_i32 v2, v2, 0, v227
	v_med3_i32 v3, v3, 0, v227
	v_lshl_add_u32 v2, v2, 2, s4
	v_lshl_add_u32 v3, v3, 2, s4
	s_waitcnt lgkmcnt(0)
	v_add_f32_e32 v98, v98, v170
	v_add_f32_e32 v99, v99, v171
	ds_read_b32 v2, v2
	ds_read_b32 v3, v3
	v_add_u32_e32 v170, 0xffffffae, v169
	v_add_u32_e32 v171, 0xffffffad, v169
	v_med3_i32 v170, v170, 0, v227
	v_med3_i32 v171, v171, 0, v227
	v_lshl_add_u32 v170, v170, 2, s4
	v_lshl_add_u32 v171, v171, 2, s4
	ds_read_b32 v170, v170
	ds_read_b32 v171, v171
	s_waitcnt lgkmcnt(2)
	v_add_f32_e32 v108, v108, v2
	v_add_f32_e32 v109, v109, v3
	v_add_u32_e32 v2, 0xffffffb0, v172
	v_add_u32_e32 v3, 0xffffffaf, v172
	v_med3_i32 v2, v2, 0, v227
	v_med3_i32 v3, v3, 0, v227
	v_lshl_add_u32 v2, v2, 2, s4
	v_lshl_add_u32 v3, v3, 2, s4
	s_waitcnt lgkmcnt(0)
	v_add_f32_e32 v110, v110, v170
	v_add_f32_e32 v111, v111, v171
	ds_read_b32 v2, v2
	ds_read_b32 v3, v3
	v_add_u32_e32 v170, 0xffffffae, v172
	v_add_u32_e32 v171, 0xffffffad, v172
	v_med3_i32 v170, v170, 0, v227
	v_med3_i32 v171, v171, 0, v227
	v_lshl_add_u32 v170, v170, 2, s4
	v_lshl_add_u32 v171, v171, 2, s4
	ds_read_b32 v170, v170
	ds_read_b32 v171, v171
	s_waitcnt lgkmcnt(2)
	v_add_f32_e32 v92, v92, v2
	v_add_f32_e32 v93, v93, v3
	v_add_u32_e32 v2, 0xffffffa0, v169
	v_add_u32_e32 v3, 0xffffff9f, v169
	v_med3_i32 v2, v2, 0, v227
	v_med3_i32 v3, v3, 0, v227
	v_lshl_add_u32 v2, v2, 2, s4
	v_lshl_add_u32 v3, v3, 2, s4
	s_waitcnt lgkmcnt(0)
	v_add_f32_e32 v94, v94, v170
	v_add_f32_e32 v95, v95, v171
	ds_read_b32 v2, v2
	ds_read_b32 v3, v3
	v_add_u32_e32 v170, 0xffffff9e, v169
	v_add_u32_e32 v171, 0xffffff9d, v169
	v_med3_i32 v170, v170, 0, v227
	v_med3_i32 v171, v171, 0, v227
	v_lshl_add_u32 v170, v170, 2, s4
	v_lshl_add_u32 v171, v171, 2, s4
	ds_read_b32 v170, v170
	ds_read_b32 v171, v171
	s_waitcnt lgkmcnt(2)
	v_add_f32_e32 v104, v104, v2
	v_add_f32_e32 v105, v105, v3
	v_add_u32_e32 v2, 0xffffffa0, v172
	v_add_u32_e32 v3, 0xffffff9f, v172
	v_med3_i32 v2, v2, 0, v227
	v_med3_i32 v3, v3, 0, v227
	v_lshl_add_u32 v2, v2, 2, s4
	v_lshl_add_u32 v3, v3, 2, s4
	s_waitcnt lgkmcnt(0)
	v_add_f32_e32 v106, v106, v170
	v_add_f32_e32 v107, v107, v171
	ds_read_b32 v2, v2
	ds_read_b32 v3, v3
	v_add_u32_e32 v170, 0xffffff9e, v172
	v_add_u32_e32 v171, 0xffffff9d, v172
	v_med3_i32 v170, v170, 0, v227
	v_med3_i32 v171, v171, 0, v227
	v_lshl_add_u32 v170, v170, 2, s4
	v_lshl_add_u32 v171, v171, 2, s4
	ds_read_b32 v170, v170
	ds_read_b32 v171, v171
	s_waitcnt lgkmcnt(2)
	v_add_f32_e32 v88, v88, v2
	v_add_f32_e32 v89, v89, v3
	v_add_u32_e32 v2, 0xffffff90, v169
	v_add_u32_e32 v3, 0xffffff8f, v169
	v_med3_i32 v2, v2, 0, v227
	v_med3_i32 v3, v3, 0, v227
	v_lshl_add_u32 v2, v2, 2, s4
	v_lshl_add_u32 v3, v3, 2, s4
	s_waitcnt lgkmcnt(0)
	v_add_f32_e32 v90, v90, v170
	v_add_f32_e32 v91, v91, v171
	ds_read_b32 v2, v2
	ds_read_b32 v3, v3
	v_add_u32_e32 v170, 0xffffff8e, v169
	v_add_u32_e32 v169, 0xffffff8d, v169
	v_med3_i32 v170, v170, 0, v227
	v_med3_i32 v169, v169, 0, v227
	v_lshl_add_u32 v170, v170, 2, s4
	v_lshl_add_u32 v169, v169, 2, s4
	ds_read_b32 v170, v170
	ds_read_b32 v171, v169
	s_waitcnt lgkmcnt(2)
	v_add_f32_e32 v100, v100, v2
	v_add_f32_e32 v101, v101, v3
	v_add_u32_e32 v2, 0xffffff90, v172
	v_add_u32_e32 v3, 0xffffff8f, v172
	v_add_u32_e32 v169, 0xffffff8e, v172
	v_med3_i32 v2, v2, 0, v227
	v_med3_i32 v3, v3, 0, v227
	v_med3_i32 v169, v169, 0, v227
	v_lshl_add_u32 v2, v2, 2, s4
	v_lshl_add_u32 v3, v3, 2, s4
	v_lshl_add_u32 v169, v169, 2, s4
	s_waitcnt lgkmcnt(0)
	v_add_f32_e32 v102, v102, v170
	v_add_f32_e32 v103, v103, v171
	ds_read_b32 v2, v2
	ds_read_b32 v3, v3
	ds_read_b32 v170, v169
	v_add_u32_e32 v169, 0xffffff8d, v172
	v_med3_i32 v169, v169, 0, v227
	v_lshl_add_u32 v169, v169, 2, s4
	ds_read_b32 v171, v169
	s_waitcnt lgkmcnt(2)
	v_add_f32_e32 v84, v84, v2
	v_add_f32_e32 v85, v85, v3
	s_waitcnt lgkmcnt(0)
	v_add_f32_e32 v86, v86, v170
	v_add_f32_e32 v87, v87, v171

; #define LAS __attribute__((address_space(3)))
; __device__ __forceinline__ unsigned pk2(float lo, float hi) { const f32x2_t v = {lo, hi}; const bf16x2_t b = __builtin_convertvector(v, bf16x2_t); return __builtin_bit_cast(unsigned, b); }
; template <bool MOBA>
; __device__ __forceinline__ void attn_unit(unsigned char* lds, LAS unsigned char* lds3, const Params& p, int b, int h, int qb) {
;     ...
;             {
; #pragma unroll
;             for (int jb = 0; jb < 2; ++jb) { float ls = 0.f;
; #pragma unroll
;                 for (int kb = 0; kb < 4; ++kb)
; #pragma unroll
;                     for (int r = 0; r < 4; ++r) { const float e = __builtin_amdgcn_exp2f(s[kb][jb][r]); s[kb][jb][r] = e; ls += e; }
;                 lrow[jb] += ls; }
;             { u32x2 vlo[2][4], vhi[2][4];
; #pragma unroll
;             for (int ks2 = 0; ks2 < 2; ++ks2)
; #pragma unroll
;                 for (int db = 0; db < 4; ++db) { const int d = 32 * (db >> 1) + 8 * (fr >> 2) + 4 * (db & 1) + (fr & 3);        const int kx = (32 * ks2 + 4 * fq) ^ (((d >> 3) & 7) << 3);
;                     vlo[ks2][db] = *(const LAS u32x2*)(Vt + slot * 4608 + d * 72 + kx); vhi[ks2][db] = *(const LAS u32x2*)(Vt + slot * 4608 + d * 72 + (kx ^ 16)); }
;             bf16x8 pf[2][2];
; #pragma unroll
;             for (int ks2 = 0; ks2 < 2; ++ks2)
; #pragma unroll
;                 for (int jb = 0; jb < 2; ++jb) { const f32x4 a = s[2 * ks2][jb], c = s[2 * ks2 + 1][jb]; u32x4 pw; pw.x = pk2(a[0], a[1]); pw.y = pk2(a[2], a[3]); pw.z = pk2(c[0], c[1]); pw.w = pk2(c[2], c[3]); pf[ks2][jb] = __builtin_bit_cast(bf16x8, pw); }
;             __builtin_amdgcn_sched_barrier(0);
; #pragma unroll
;             for (int ks2 = 0; ks2 < 2; ++ks2)
; #pragma unroll
;                 for (int db = 0; db < 4; ++db) { u32x4 vv; vv.x = vlo[ks2][db].x; vv.y = vlo[ks2][db].y; vv.z = vhi[ks2][db].x; vv.w = vhi[ks2][db].y; const bf16x8 vf = __builtin_bit_cast(bf16x8, vv);
;                     o[db][0] = __builtin_amdgcn_mfma_f32_16x16x32_bf16(vf, pf[ks2][0], o[db][0], 0, 0, 0); o[db][1] = __builtin_amdgcn_mfma_f32_16x16x32_bf16(vf, pf[ks2][1], o[db][1], 0, 0, 0); }
.LBB0_483:
	v_exp_f32_e32 v3, v112
	v_exp_f32_e32 v2, v96
	v_exp_f32_e32 v181, v113
	v_exp_f32_e32 v180, v97
	v_exp_f32_e32 v183, v114
	v_exp_f32_e32 v182, v98
	v_exp_f32_e32 v185, v115
	v_exp_f32_e32 v184, v99
	v_exp_f32_e32 v187, v108
	v_exp_f32_e32 v186, v92
	v_exp_f32_e32 v194, v88
	v_exp_f32_e32 v196, v89
	v_add_f32_e32 v88, 0, v2
	v_add_f32_e32 v89, 0, v3
	v_exp_f32_e32 v189, v109
	v_exp_f32_e32 v188, v93
	v_add_f32_e32 v88, v180, v88
	v_add_f32_e32 v89, v181, v89
	v_exp_f32_e32 v191, v110
	v_exp_f32_e32 v190, v94
	v_add_f32_e32 v88, v182, v88
	v_add_f32_e32 v89, v183, v89
	v_exp_f32_e32 v193, v111
	v_exp_f32_e32 v192, v95
	v_add_f32_e32 v88, v184, v88
	v_add_f32_e32 v89, v185, v89
	v_exp_f32_e32 v195, v104
	v_add_f32_e32 v88, v186, v88
	v_add_f32_e32 v89, v187, v89
	v_exp_f32_e32 v197, v105
	v_add_f32_e32 v88, v188, v88
	v_add_f32_e32 v89, v189, v89
	v_exp_f32_e32 v199, v106
	v_add_f32_e32 v88, v190, v88
	v_add_f32_e32 v89, v191, v89
	v_exp_f32_e32 v198, v90
	v_exp_f32_e32 v201, v107
	v_add_f32_e32 v88, v192, v88
	v_add_f32_e32 v89, v193, v89
	v_exp_f32_e32 v200, v91
	v_exp_f32_e32 v203, v100
	v_add_f32_e32 v88, v194, v88
	v_add_f32_e32 v89, v195, v89
	v_exp_f32_e32 v202, v84
	v_exp_f32_e32 v205, v101
	v_add_f32_e32 v88, v196, v88
	v_add_f32_e32 v89, v197, v89
	v_exp_f32_e32 v204, v85
	v_exp_f32_e32 v207, v102
	v_exp_f32_e32 v206, v86
	v_add_f32_e32 v84, v198, v88
	v_add_f32_e32 v85, v199, v89
	v_exp_f32_e32 v209, v103
	v_exp_f32_e32 v208, v87
	v_add_f32_e32 v84, v200, v84
	v_add_f32_e32 v85, v201, v85
	s_add_i32 s4, s6, 0
	v_add_f32_e32 v84, v202, v84
	v_add_f32_e32 v85, v203, v85
	v_add_u32_e32 v100, s4, v157
	v_add_f32_e32 v84, v204, v84
	v_add_f32_e32 v85, v205, v85
	v_lshlrev_b32_e32 v86, 1, v158
	v_add_f32_e32 v84, v206, v84
	v_add_f32_e32 v85, v207, v85
	v_add_u32_e32 v101, s4, v159
	v_add_f32_e32 v84, v208, v84
	v_add_f32_e32 v85, v209, v85
	v_add_u32_e32 v108, s4, v161
	v_add_f32_e32 v126, v126, v84
	v_add_f32_e32 v127, v127, v85
	v_lshlrev_b32_e32 v84, 1, v156
	v_lshlrev_b32_e32 v92, 1, v160
	v_lshlrev_b32_e32 v94, 1, v162
	v_add_u32_e32 v109, s4, v163
	v_lshlrev_b32_e32 v102, 1, v164
	v_lshlrev_b32_e32 v104, 1, v165
	v_lshlrev_b32_e32 v110, 1, v166
	v_lshlrev_b32_e32 v112, 1, v167
	v_add_u32_e32 v85, v100, v84
	v_add_u32_e32 v87, v100, v86
	v_add_u32_e32 v88, v101, v84
	v_add_u32_e32 v90, v101, v86
	v_add_u32_e32 v93, v108, v92
	v_add_u32_e32 v95, v108, v94
	v_add_u32_e32 v96, v109, v92
	v_add_u32_e32 v98, v109, v94
	v_add_u32_e32 v103, v100, v102
	v_add_u32_e32 v105, v100, v104
	v_add_u32_e32 v106, v101, v102
	v_add_u32_e32 v107, v101, v104
	v_add_u32_e32 v111, v108, v110
	v_add_u32_e32 v113, v108, v112
	v_add_u32_e32 v114, v109, v110
	v_add_u32_e32 v115, v109, v112
	ds_read_b64 v[84:85], v85 offset:36864
	ds_read_b64 v[86:87], v87 offset:36864
	ds_read_b64 v[88:89], v88 offset:36864
	ds_read_b64 v[90:91], v90 offset:36864
	ds_read_b64 v[92:93], v93 offset:36864
	ds_read_b64 v[94:95], v95 offset:36864
	ds_read_b64 v[96:97], v96 offset:36864
	ds_read_b64 v[98:99], v98 offset:36864
	ds_read_b64 v[100:101], v103 offset:36864
	ds_read_b64 v[102:103], v105 offset:36864
	ds_read_b64 v[104:105], v106 offset:36864
	ds_read_b64 v[106:107], v107 offset:36864
	ds_read_b64 v[108:109], v111 offset:36864
	ds_read_b64 v[110:111], v113 offset:36864
	ds_read_b64 v[112:113], v114 offset:36864
	ds_read_b64 v[114:115], v115 offset:36864
	v_cvt_pk_bf16_f32 v170, v3, v181
	v_cvt_pk_bf16_f32 v171, v183, v185
	v_cvt_pk_bf16_f32 v172, v187, v189
	v_cvt_pk_bf16_f32 v173, v191, v193
	v_cvt_pk_bf16_f32 v180, v2, v180
	v_cvt_pk_bf16_f32 v181, v182, v184
	v_cvt_pk_bf16_f32 v182, v186, v188
	v_cvt_pk_bf16_f32 v183, v190, v192
	v_cvt_pk_bf16_f32 v184, v195, v197
	v_cvt_pk_bf16_f32 v185, v199, v201
	v_cvt_pk_bf16_f32 v186, v203, v205
	v_cvt_pk_bf16_f32 v187, v207, v209
	v_cvt_pk_bf16_f32 v188, v194, v196
	v_cvt_pk_bf16_f32 v189, v198, v200
	v_cvt_pk_bf16_f32 v190, v202, v204
	v_cvt_pk_bf16_f32 v191, v206, v208
	s_waitcnt lgkmcnt(14)
	v_mfma_f32_16x16x32_bf16 v[80:83], v[84:87], v[170:173], v[80:83]
	v_mfma_f32_16x16x32_bf16 v[64:67], v[84:87], v[180:183], v[64:67]
	s_waitcnt lgkmcnt(12)
	v_mfma_f32_16x16x32_bf16 v[76:79], v[88:91], v[170:173], v[76:79]
	v_mfma_f32_16x16x32_bf16 v[60:63], v[88:91], v[180:183], v[60:63]
	s_waitcnt lgkmcnt(10)
	v_mfma_f32_16x16x32_bf16 v[72:75], v[92:95], v[170:173], v[72:75]
	v_mfma_f32_16x16x32_bf16 v[56:59], v[92:95], v[180:183], v[56:59]
	s_waitcnt lgkmcnt(8)
	v_mfma_f32_16x16x32_bf16 v[68:71], v[96:99], v[170:173], v[68:71]
	v_mfma_f32_16x16x32_bf16 v[52:55], v[96:99], v[180:183], v[52:55]
	s_waitcnt lgkmcnt(6)
	v_mfma_f32_16x16x32_bf16 v[80:83], v[100:103], v[184:187], v[80:83]
	v_mfma_f32_16x16x32_bf16 v[64:67], v[100:103], v[188:191], v[64:67]
	s_waitcnt lgkmcnt(4)
	v_mfma_f32_16x16x32_bf16 v[76:79], v[104:107], v[184:187], v[76:79]
	v_mfma_f32_16x16x32_bf16 v[60:63], v[104:107], v[188:191], v[60:63]
	s_waitcnt lgkmcnt(2)
	v_mfma_f32_16x16x32_bf16 v[72:75], v[108:111], v[184:187], v[72:75]
	v_mfma_f32_16x16x32_bf16 v[56:59], v[108:111], v[188:191], v[56:59]
	s_waitcnt lgkmcnt(0)
	v_mfma_f32_16x16x32_bf16 v[68:71], v[112:115], v[184:187], v[68:71]
	v_mfma_f32_16x16x32_bf16 v[52:55], v[112:115], v[188:191], v[52:55]
	s_cmp_le_i32 s27, s21
	s_cselect_b64 s[16:17], -1, 0
	s_cmp_gt_i32 s27, -1
	s_cbranch_scc1 .LBB0_486

; #define LAS __attribute__((address_space(3)))
; template <bool MOBA>
; __device__ __forceinline__ void attn_unit(unsigned char* lds, LAS unsigned char* lds3, const Params& p, int b, int h, int qb) {
;     ...
;             const bool diag = (tl == (w >> 1));
;             f32x4 s[4][2];
;             bool band = false;
;             if (!MOBA) {
;                 const float f0 = fq2[0] - mref[0], f1 = fq2[1] - mref[1];
; #pragma unroll
;                 for (int kb = 0; kb < 4; ++kb) { const f32x4 fk = *(const LAS f32x4*)(Fs + 64 * t + 16 * kb + 4 * fq); s[kb][0] = f0 - fk; s[kb][1] = f1 - fk; }
;             } else {
;                 band = (t >> 2) >= qb - 1;
;                 const float cc = band ? 0.f : c31;
;                 const float c0 = (qv[0] ? cc : NEGBIG) - mrc[0], c1 = (qv[1] ? cc : NEGBIG) - mrc[1];
; #pragma unroll
;                 for (int kb = 0; kb < 4; ++kb) { s[kb][0] = (f32x4){c0, c0, c0, c0}; s[kb][1] = (f32x4){c1, c1, c1, c1}; }
;             }
;             { bf16x8 kf[4][2];
; #pragma unroll
;             for (int kb = 0; kb < 4; ++kb)
; #pragma unroll
;                 for (int ks = 0; ks < 2; ++ks) kf[kb][ks] = *(const LAS bf16x8*)(Ks + slot * 4608 + (16 * kb + fr) * 72 + 32 * ks + 8 * fq);
;             __builtin_amdgcn_sched_barrier(0);
; #pragma unroll
;             for (int kb = 0; kb < 4; ++kb)
; #pragma unroll
;                 for (int ks = 0; ks < 2; ++ks) {
;                     s[kb][0] = __builtin_amdgcn_mfma_f32_16x16x32_bf16(kf[kb][ks], qf[0][ks], s[kb][0], 0, 0, 0); s[kb][1] = __builtin_amdgcn_mfma_f32_16x16x32_bf16(kf[kb][ks], qf[1][ks], s[kb][1], 0, 0, 0); }
;             __builtin_amdgcn_sched_barrier(0); }
;             if (MOBA && band) {
;                 asm volatile("" ::: "memory");
; #pragma unroll
;                 for (int kb = 0; kb < 4; ++kb)
; #pragma unroll
;                     for (int jb = 0; jb < 2; ++jb)
; #pragma unroll
;                         for (int r = 0; r < 4; ++r) { int d = (256 * qb + qpl[jb]) - (64 * t + 16 * kb + 4 * fq + r); d = d < 0 ? 0 : (d > 127 ? 127 : d); s[kb][jb][r] += tbl[d]; }
;             }
.LBB0_487:
	ds_read_b128 v[88:91], v1 offset:9216
	ds_read_b128 v[92:95], v1 offset:9280
	ds_read_b128 v[104:107], v1 offset:11520
	ds_read_b128 v[170:173], v1 offset:11584
	ds_read_b128 v[180:183], v1 offset:13824
	ds_read_b128 v[184:187], v1 offset:13888
	ds_read_b128 v[188:191], v1 offset:16128
	ds_read_b128 v[192:195], v1 offset:16192
	s_ashr_i32 s4, s28, 2
	s_cmp_lt_i32 s4, s20
	s_cselect_b64 vcc, -1, 0
	v_cndmask_b32_e32 v2, 0, v133, vcc
	v_cndmask_b32_e64 v3, v226, v2, s[10:11]
	v_cndmask_b32_e64 v2, v226, v2, s[12:13]
	v_sub_f32_e32 v84, v3, v122
	s_waitcnt lgkmcnt(8)
	v_sub_f32_e32 v100, v2, v123
	v_mov_b32_e32 v85, v84
	v_mov_b32_e32 v86, v84
	v_mov_b32_e32 v87, v84
	v_mov_b32_e32 v101, v100
	v_mov_b32_e32 v102, v100
	v_mov_b32_e32 v103, v100
	s_waitcnt lgkmcnt(7)
	v_mfma_f32_16x16x32_bf16 v[96:99], v[88:91], v[8:11], v[84:87]
	v_mfma_f32_16x16x32_bf16 v[88:91], v[88:91], v[16:19], v[100:103]
	s_waitcnt lgkmcnt(6)
	v_mfma_f32_16x16x32_bf16 v[112:115], v[92:95], v[4:7], v[96:99]
	v_mfma_f32_16x16x32_bf16 v[96:99], v[92:95], v[12:15], v[88:91]
	s_waitcnt lgkmcnt(5)
	v_mfma_f32_16x16x32_bf16 v[88:91], v[104:107], v[8:11], v[84:87]
	v_mfma_f32_16x16x32_bf16 v[92:95], v[104:107], v[16:19], v[100:103]
	s_waitcnt lgkmcnt(4)
	v_mfma_f32_16x16x32_bf16 v[108:111], v[170:173], v[4:7], v[88:91]
	v_mfma_f32_16x16x32_bf16 v[92:95], v[170:173], v[12:15], v[92:95]
	s_waitcnt lgkmcnt(3)
	v_mfma_f32_16x16x32_bf16 v[88:91], v[180:183], v[8:11], v[84:87]
	v_mfma_f32_16x16x32_bf16 v[170:173], v[180:183], v[16:19], v[100:103]
	s_waitcnt lgkmcnt(2)
	v_mfma_f32_16x16x32_bf16 v[104:107], v[184:187], v[4:7], v[88:91]
	v_mfma_f32_16x16x32_bf16 v[88:91], v[184:187], v[12:15], v[170:173]
	s_waitcnt lgkmcnt(1)
	v_mfma_f32_16x16x32_bf16 v[84:87], v[188:191], v[8:11], v[84:87]
	v_mfma_f32_16x16x32_bf16 v[170:173], v[188:191], v[16:19], v[100:103]
	s_waitcnt lgkmcnt(0)
	v_mfma_f32_16x16x32_bf16 v[100:103], v[192:195], v[4:7], v[84:87]
	v_mfma_f32_16x16x32_bf16 v[84:87], v[192:195], v[12:15], v[170:173]
	s_and_b64 vcc, exec, vcc
	s_cbranch_vccnz .LBB0_489
	v_add3_u32 v1, v139, v124, s24
	v_add_u32_e32 v3, -1, v1
	v_add_u32_e32 v169, -2, v1
	v_med3_i32 v2, v1, 0, v227
	s_add_i32 s4, 0, 0x13000
	v_med3_i32 v3, v3, 0, v227
	v_med3_i32 v169, v169, 0, v227
	v_lshl_add_u32 v2, v2, 2, s4
	v_lshl_add_u32 v3, v3, 2, s4
	v_lshl_add_u32 v169, v169, 2, s4
	ds_read_b32 v2, v2
	ds_read_b32 v3, v3
	ds_read_b32 v170, v169
	v_add_u32_e32 v169, -3, v1
	v_med3_i32 v169, v169, 0, v227
	v_lshl_add_u32 v169, v169, 2, s4
	ds_read_b32 v171, v169
	v_add3_u32 v169, v139, v125, s24
	s_waitcnt lgkmcnt(2)
	v_add_f32_e32 v112, v112, v2
	v_add_f32_e32 v113, v113, v3
	v_add_u32_e32 v3, -1, v169
	v_med3_i32 v2, v169, 0, v227
	v_med3_i32 v3, v3, 0, v227
	v_lshl_add_u32 v2, v2, 2, s4
	v_lshl_add_u32 v3, v3, 2, s4
	s_waitcnt lgkmcnt(0)
	v_add_f32_e32 v114, v114, v170
	v_add_f32_e32 v115, v115, v171
	ds_read_b32 v2, v2
	ds_read_b32 v3, v3
	v_add_u32_e32 v170, -2, v169
	v_add_u32_e32 v171, -3, v169
	v_med3_i32 v170, v170, 0, v227
	v_med3_i32 v171, v171, 0, v227
	v_lshl_add_u32 v170, v170, 2, s4
	v_lshl_add_u32 v171, v171, 2, s4
	ds_read_b32 v170, v170
	ds_read_b32 v171, v171
	s_waitcnt lgkmcnt(2)
	v_add_f32_e32 v96, v96, v2
	v_add_f32_e32 v97, v97, v3
	v_add_u32_e32 v2, -16, v1
	v_subrev_u32_e32 v3, 17, v1
	v_med3_i32 v2, v2, 0, v227
	v_med3_i32 v3, v3, 0, v227
	v_lshl_add_u32 v2, v2, 2, s4
	v_lshl_add_u32 v3, v3, 2, s4
	s_waitcnt lgkmcnt(0)
	v_add_f32_e32 v98, v98, v170
	v_add_f32_e32 v99, v99, v171
	ds_read_b32 v2, v2
	ds_read_b32 v3, v3
	v_subrev_u32_e32 v170, 18, v1
	v_subrev_u32_e32 v171, 19, v1
	v_med3_i32 v170, v170, 0, v227
	v_med3_i32 v171, v171, 0, v227
	v_lshl_add_u32 v170, v170, 2, s4
	v_lshl_add_u32 v171, v171, 2, s4
	ds_read_b32 v170, v170
	ds_read_b32 v171, v171
	s_waitcnt lgkmcnt(2)
	v_add_f32_e32 v108, v108, v2
	v_add_f32_e32 v109, v109, v3
	v_add_u32_e32 v2, -16, v169
	v_subrev_u32_e32 v3, 17, v169
	v_med3_i32 v2, v2, 0, v227
	v_med3_i32 v3, v3, 0, v227
	v_lshl_add_u32 v2, v2, 2, s4
	v_lshl_add_u32 v3, v3, 2, s4
	s_waitcnt lgkmcnt(0)
	v_add_f32_e32 v110, v110, v170
	v_add_f32_e32 v111, v111, v171
	ds_read_b32 v2, v2
	ds_read_b32 v3, v3
	v_subrev_u32_e32 v170, 18, v169
	v_subrev_u32_e32 v171, 19, v169
	v_med3_i32 v170, v170, 0, v227
	v_med3_i32 v171, v171, 0, v227
	v_lshl_add_u32 v170, v170, 2, s4
	v_lshl_add_u32 v171, v171, 2, s4
	ds_read_b32 v170, v170
	ds_read_b32 v171, v171
	s_waitcnt lgkmcnt(2)
	v_add_f32_e32 v92, v92, v2
	v_add_f32_e32 v93, v93, v3
	v_subrev_u32_e32 v2, 32, v1
	v_subrev_u32_e32 v3, 33, v1
	v_med3_i32 v2, v2, 0, v227
	v_med3_i32 v3, v3, 0, v227
	v_lshl_add_u32 v2, v2, 2, s4
	v_lshl_add_u32 v3, v3, 2, s4
	s_waitcnt lgkmcnt(0)
	v_add_f32_e32 v94, v94, v170
	v_add_f32_e32 v95, v95, v171
	ds_read_b32 v2, v2
	ds_read_b32 v3, v3
	v_subrev_u32_e32 v170, 34, v1
	v_subrev_u32_e32 v171, 35, v1
	v_med3_i32 v170, v170, 0, v227
	v_med3_i32 v171, v171, 0, v227
	v_lshl_add_u32 v170, v170, 2, s4
	v_lshl_add_u32 v171, v171, 2, s4
	ds_read_b32 v170, v170
	ds_read_b32 v171, v171
	s_waitcnt lgkmcnt(2)
	v_add_f32_e32 v104, v104, v2
	v_add_f32_e32 v105, v105, v3
	v_subrev_u32_e32 v2, 32, v169
	v_subrev_u32_e32 v3, 33, v169
	v_med3_i32 v2, v2, 0, v227
	v_med3_i32 v3, v3, 0, v227
	v_lshl_add_u32 v2, v2, 2, s4
	v_lshl_add_u32 v3, v3, 2, s4
	s_waitcnt lgkmcnt(0)
	v_add_f32_e32 v106, v106, v170
	v_add_f32_e32 v107, v107, v171
	ds_read_b32 v2, v2
	ds_read_b32 v3, v3
	v_subrev_u32_e32 v170, 34, v169
	v_subrev_u32_e32 v171, 35, v169
	v_med3_i32 v170, v170, 0, v227
	v_med3_i32 v171, v171, 0, v227
	v_lshl_add_u32 v170, v170, 2, s4
	v_lshl_add_u32 v171, v171, 2, s4
	ds_read_b32 v170, v170
	ds_read_b32 v171, v171
	s_waitcnt lgkmcnt(2)
	v_add_f32_e32 v88, v88, v2
	v_add_f32_e32 v89, v89, v3
	v_subrev_u32_e32 v2, 48, v1
	v_subrev_u32_e32 v3, 49, v1
	v_med3_i32 v2, v2, 0, v227
	v_med3_i32 v3, v3, 0, v227
	v_lshl_add_u32 v2, v2, 2, s4
	v_lshl_add_u32 v3, v3, 2, s4
	ds_read_b32 v2, v2
	ds_read_b32 v3, v3
	s_waitcnt lgkmcnt(2)
	v_add_f32_e32 v90, v90, v170
	v_add_f32_e32 v91, v91, v171
	v_subrev_u32_e32 v170, 50, v1
	v_subrev_u32_e32 v1, 51, v1
	v_med3_i32 v1, v1, 0, v227
	v_lshl_add_u32 v1, v1, 2, s4
	ds_read_b32 v171, v1
	v_subrev_u32_e32 v1, 48, v169
	v_med3_i32 v170, v170, 0, v227
	v_med3_i32 v1, v1, 0, v227
	v_lshl_add_u32 v170, v170, 2, s4
	v_lshl_add_u32 v1, v1, 2, s4
	ds_read_b32 v170, v170
	s_waitcnt lgkmcnt(2)
	v_add_f32_e32 v100, v100, v2
	v_add_f32_e32 v101, v101, v3
	ds_read_b32 v2, v1
	v_subrev_u32_e32 v1, 49, v169
	v_med3_i32 v1, v1, 0, v227
	v_lshl_add_u32 v1, v1, 2, s4
	ds_read_b32 v3, v1
	v_subrev_u32_e32 v1, 50, v169
	v_med3_i32 v1, v1, 0, v227
	v_lshl_add_u32 v1, v1, 2, s4
	s_waitcnt lgkmcnt(2)
	v_add_f32_e32 v102, v102, v170
	v_add_f32_e32 v103, v103, v171
	ds_read_b32 v170, v1
	v_subrev_u32_e32 v1, 51, v169
	v_med3_i32 v1, v1, 0, v227
	v_lshl_add_u32 v1, v1, 2, s4
	ds_read_b32 v171, v1
	s_waitcnt lgkmcnt(2)
	v_add_f32_e32 v84, v84, v2
	v_add_f32_e32 v85, v85, v3
	s_waitcnt lgkmcnt(0)
	v_add_f32_e32 v86, v86, v170
	v_add_f32_e32 v87, v87, v171

; #define LAS __attribute__((address_space(3)))
; __device__ __forceinline__ unsigned pk2(float lo, float hi) { const f32x2_t v = {lo, hi}; const bf16x2_t b = __builtin_convertvector(v, bf16x2_t); return __builtin_bit_cast(unsigned, b); }
; template <bool MOBA>
; __device__ __forceinline__ void attn_unit(unsigned char* lds, LAS unsigned char* lds3, const Params& p, int b, int h, int qb) {
;     ...
;             {
; #pragma unroll
;             for (int jb = 0; jb < 2; ++jb) { float ls = 0.f;
; #pragma unroll
;                 for (int kb = 0; kb < 4; ++kb)
; #pragma unroll
;                     for (int r = 0; r < 4; ++r) { const float e = __builtin_amdgcn_exp2f(s[kb][jb][r]); s[kb][jb][r] = e; ls += e; }
;                 lrow[jb] += ls; }
;             { u32x2 vlo[2][4], vhi[2][4];
; #pragma unroll
;             for (int ks2 = 0; ks2 < 2; ++ks2)
; #pragma unroll
;                 for (int db = 0; db < 4; ++db) { const int d = 32 * (db >> 1) + 8 * (fr >> 2) + 4 * (db & 1) + (fr & 3);        const int kx = (32 * ks2 + 4 * fq) ^ (((d >> 3) & 7) << 3);
;                     vlo[ks2][db] = *(const LAS u32x2*)(Vt + slot * 4608 + d * 72 + kx); vhi[ks2][db] = *(const LAS u32x2*)(Vt + slot * 4608 + d * 72 + (kx ^ 16)); }
;             bf16x8 pf[2][2];
; #pragma unroll
;             for (int ks2 = 0; ks2 < 2; ++ks2)
; #pragma unroll
;                 for (int jb = 0; jb < 2; ++jb) { const f32x4 a = s[2 * ks2][jb], c = s[2 * ks2 + 1][jb]; u32x4 pw; pw.x = pk2(a[0], a[1]); pw.y = pk2(a[2], a[3]); pw.z = pk2(c[0], c[1]); pw.w = pk2(c[2], c[3]); pf[ks2][jb] = __builtin_bit_cast(bf16x8, pw); }
;             __builtin_amdgcn_sched_barrier(0);
; #pragma unroll
;             for (int ks2 = 0; ks2 < 2; ++ks2)
; #pragma unroll
;                 for (int db = 0; db < 4; ++db) { u32x4 vv; vv.x = vlo[ks2][db].x; vv.y = vlo[ks2][db].y; vv.z = vhi[ks2][db].x; vv.w = vhi[ks2][db].y; const bf16x8 vf = __builtin_bit_cast(bf16x8, vv);
;                     o[db][0] = __builtin_amdgcn_mfma_f32_16x16x32_bf16(vf, pf[ks2][0], o[db][0], 0, 0, 0); o[db][1] = __builtin_amdgcn_mfma_f32_16x16x32_bf16(vf, pf[ks2][1], o[db][1], 0, 0, 0); }
.LBB0_491:
	v_exp_f32_e32 v3, v112
	v_exp_f32_e32 v2, v96
	v_exp_f32_e32 v181, v113
	v_exp_f32_e32 v180, v97
	v_exp_f32_e32 v183, v114
	v_exp_f32_e32 v182, v98
	v_exp_f32_e32 v185, v115
	v_exp_f32_e32 v184, v99
	v_exp_f32_e32 v187, v108
	v_exp_f32_e32 v186, v92
	v_exp_f32_e32 v188, v93
	v_add_f32_e32 v92, 0, v2
	v_add_f32_e32 v93, 0, v3
	v_exp_f32_e32 v189, v109
	v_add_f32_e32 v92, v180, v92
	v_add_f32_e32 v93, v181, v93
	v_exp_f32_e32 v191, v110
	v_exp_f32_e32 v190, v94
	v_add_f32_e32 v92, v182, v92
	v_add_f32_e32 v93, v183, v93
	v_exp_f32_e32 v193, v111
	v_exp_f32_e32 v192, v95
	v_add_f32_e32 v92, v184, v92
	v_add_f32_e32 v93, v185, v93
	v_exp_f32_e32 v195, v104
	v_add_f32_e32 v92, v186, v92
	v_add_f32_e32 v93, v187, v93
	v_exp_f32_e32 v194, v88
	v_exp_f32_e32 v197, v105
	v_add_f32_e32 v92, v188, v92
	v_add_f32_e32 v93, v189, v93
	v_exp_f32_e32 v196, v89
	v_exp_f32_e32 v199, v106
	v_add_f32_e32 v92, v190, v92
	v_add_f32_e32 v93, v191, v93
	v_exp_f32_e32 v198, v90
	v_exp_f32_e32 v201, v107
	v_add_f32_e32 v92, v192, v92
	v_add_f32_e32 v93, v193, v93
	v_exp_f32_e32 v200, v91
	v_exp_f32_e32 v203, v100
	v_exp_f32_e32 v202, v84
	v_exp_f32_e32 v204, v85
	v_add_f32_e32 v84, v194, v92
	v_add_f32_e32 v85, v195, v93
	v_exp_f32_e32 v205, v101
	v_add_f32_e32 v84, v196, v84
	v_add_f32_e32 v85, v197, v85
	v_exp_f32_e32 v207, v102
	v_exp_f32_e32 v206, v86
	v_add_f32_e32 v84, v198, v84
	v_add_f32_e32 v85, v199, v85
	v_exp_f32_e32 v209, v103
	v_exp_f32_e32 v208, v87
	v_add_f32_e32 v84, v200, v84
	v_add_f32_e32 v85, v201, v85
	s_add_i32 s4, s6, 0
	v_add_f32_e32 v84, v202, v84
	v_add_f32_e32 v85, v203, v85
	v_add_u32_e32 v1, s4, v157
	v_add_f32_e32 v84, v204, v84
	v_add_f32_e32 v85, v205, v85
	v_lshlrev_b32_e32 v86, 1, v158
	v_add_f32_e32 v84, v206, v84
	v_add_f32_e32 v85, v207, v85
	v_add_u32_e32 v100, s4, v159
	v_add_f32_e32 v84, v208, v84
	v_add_f32_e32 v85, v209, v85
	v_add_u32_e32 v108, s4, v161
	v_add_f32_e32 v126, v126, v84
	v_add_f32_e32 v127, v127, v85
	v_lshlrev_b32_e32 v84, 1, v156
	v_lshlrev_b32_e32 v92, 1, v160
	v_lshlrev_b32_e32 v94, 1, v162
	v_add_u32_e32 v109, s4, v163
	v_lshlrev_b32_e32 v101, 1, v164
	v_lshlrev_b32_e32 v103, 1, v165
	v_add_u32_e32 v85, v1, v84
	v_add_u32_e32 v87, v1, v86
	v_add_u32_e32 v88, v100, v84
	v_add_u32_e32 v90, v100, v86
	v_add_u32_e32 v93, v108, v92
	v_add_u32_e32 v95, v108, v94
	v_add_u32_e32 v96, v109, v92
	v_add_u32_e32 v98, v109, v94
	v_add_u32_e32 v102, v1, v101
	v_add_u32_e32 v1, v1, v103
	v_add_u32_e32 v104, v100, v101
	v_add_u32_e32 v106, v100, v103
	ds_read_b64 v[84:85], v85 offset:46080
	ds_read_b64 v[86:87], v87 offset:46080
	ds_read_b64 v[88:89], v88 offset:46080
	ds_read_b64 v[90:91], v90 offset:46080
	ds_read_b64 v[92:93], v93 offset:46080
	ds_read_b64 v[94:95], v95 offset:46080
	ds_read_b64 v[96:97], v96 offset:46080
	ds_read_b64 v[98:99], v98 offset:46080
	ds_read_b64 v[100:101], v102 offset:46080
	ds_read_b64 v[102:103], v1 offset:46080
	ds_read_b64 v[104:105], v104 offset:46080
	ds_read_b64 v[106:107], v106 offset:46080
	v_lshlrev_b32_e32 v1, 1, v166
	v_lshlrev_b32_e32 v111, 1, v167
	v_add_u32_e32 v110, v108, v1
	v_add_u32_e32 v112, v108, v111
	v_add_u32_e32 v114, v109, v111
	v_add_u32_e32 v1, v109, v1
	ds_read_b64 v[108:109], v110 offset:46080
	ds_read_b64 v[110:111], v112 offset:46080
	ds_read_b64 v[112:113], v1 offset:46080
	ds_read_b64 v[114:115], v114 offset:46080
	v_cvt_pk_bf16_f32 v170, v3, v181
	v_cvt_pk_bf16_f32 v171, v183, v185
	v_cvt_pk_bf16_f32 v172, v187, v189
	v_cvt_pk_bf16_f32 v173, v191, v193
	v_cvt_pk_bf16_f32 v180, v2, v180
	v_cvt_pk_bf16_f32 v181, v182, v184
	v_cvt_pk_bf16_f32 v182, v186, v188
	v_cvt_pk_bf16_f32 v183, v190, v192
	v_cvt_pk_bf16_f32 v184, v195, v197
	v_cvt_pk_bf16_f32 v185, v199, v201
	v_cvt_pk_bf16_f32 v186, v203, v205
	v_cvt_pk_bf16_f32 v187, v207, v209
	v_cvt_pk_bf16_f32 v188, v194, v196
	v_cvt_pk_bf16_f32 v189, v198, v200
	v_cvt_pk_bf16_f32 v190, v202, v204
	v_cvt_pk_bf16_f32 v191, v206, v208
	s_waitcnt lgkmcnt(14)
	v_mfma_f32_16x16x32_bf16 v[80:83], v[84:87], v[170:173], v[80:83]
	v_mfma_f32_16x16x32_bf16 v[64:67], v[84:87], v[180:183], v[64:67]
	s_waitcnt lgkmcnt(12)
	v_mfma_f32_16x16x32_bf16 v[76:79], v[88:91], v[170:173], v[76:79]
	v_mfma_f32_16x16x32_bf16 v[60:63], v[88:91], v[180:183], v[60:63]
	s_waitcnt lgkmcnt(10)
	v_mfma_f32_16x16x32_bf16 v[72:75], v[92:95], v[170:173], v[72:75]
	v_mfma_f32_16x16x32_bf16 v[56:59], v[92:95], v[180:183], v[56:59]
	s_waitcnt lgkmcnt(8)
	v_mfma_f32_16x16x32_bf16 v[68:71], v[96:99], v[170:173], v[68:71]
	v_mfma_f32_16x16x32_bf16 v[52:55], v[96:99], v[180:183], v[52:55]
	s_waitcnt lgkmcnt(6)
	v_mfma_f32_16x16x32_bf16 v[80:83], v[100:103], v[184:187], v[80:83]
	v_mfma_f32_16x16x32_bf16 v[64:67], v[100:103], v[188:191], v[64:67]
	s_waitcnt lgkmcnt(4)
	v_mfma_f32_16x16x32_bf16 v[76:79], v[104:107], v[184:187], v[76:79]
	v_mfma_f32_16x16x32_bf16 v[60:63], v[104:107], v[188:191], v[60:63]
	s_waitcnt lgkmcnt(2)
	v_mfma_f32_16x16x32_bf16 v[72:75], v[108:111], v[184:187], v[72:75]
	v_mfma_f32_16x16x32_bf16 v[56:59], v[108:111], v[188:191], v[56:59]
	s_waitcnt lgkmcnt(0)
	v_mfma_f32_16x16x32_bf16 v[68:71], v[112:115], v[184:187], v[68:71]
	v_mfma_f32_16x16x32_bf16 v[52:55], v[112:115], v[188:191], v[52:55]
; #define LAS __attribute__((address_space(3)))
; template <bool MOBA>
; __device__ __forceinline__ void attn_unit(unsigned char* lds, LAS unsigned char* lds3, const Params& p, int b, int h, int qb) {
;     ...
;         if (MOBA && (t & 3) == 0 && (tl >= 0 || active)) {
; #pragma unroll
;             for (int jb = 0; jb < 2; ++jb) { float l = lrow[jb]; l += __shfl_xor(l, 16); l += __shfl_xor(l, 32);
;                 if (qv[jb]) { LAS float* st = pst + qpl[jb] * 68;
; #pragma unroll
;                     for (int db = 0; db < 4; ++db) { f32x4 ov = o[db][jb]; asm volatile("" : "+v"(ov)); f32x4 v = *(const LAS f32x4*)(st + 32 * (db >> 1) + 8 * fq + 4 * (db & 1)); v += ov; *(LAS f32x4*)(st + 32 * (db >> 1) + 8 * fq + 4 * (db & 1)) = v; }
;                     if (fq == 0) st[64] += l; }
; #pragma unroll
;                 for (int db = 0; db < 4; ++db) o[db][jb] = (f32x4){0.f, 0.f, 0.f, 0.f};
;                 lrow[jb] = 0.f; }
;         }
.LBB0_492:
	s_bitcmp1_b32 s28, 1
	s_cselect_b64 s[4:5], -1, 0
	s_cmp_lt_i32 s27, 0
	s_cselect_b64 s[6:7], -1, 0
	s_xor_b64 s[16:17], s[16:17], -1
	s_and_b64 s[6:7], s[6:7], s[16:17]
	s_or_b64 s[4:5], s[4:5], s[6:7]
	s_and_b64 vcc, exec, s[4:5]
	s_cbranch_vccnz .LBB0_500
	ds_bpermute_b32 v1, v136, v127
	s_waitcnt lgkmcnt(0)
	v_add_f32_e32 v2, v127, v1
	ds_bpermute_b32 v3, v137, v2
	s_and_saveexec_b64 s[6:7], s[10:11]
	s_cbranch_execz .LBB0_496
	v_mul_lo_u32 v1, v124, s62
	v_add_u32_e32 v1, s61, v1
	v_add_u32_e32 v88, v1, v168
	ds_read_b128 v[84:87], v88
	s_waitcnt lgkmcnt(0)
	v_add_f32_e32 v82, v82, v86
	v_add_f32_e32 v83, v83, v87
	v_add_f32_e32 v80, v80, v84
	v_add_f32_e32 v81, v81, v85
	ds_write_b128 v88, v[80:83]
	ds_read_b128 v[80:83], v88 offset:16
	s_waitcnt lgkmcnt(0)
	v_add_f32_e32 v78, v78, v82
	v_add_f32_e32 v79, v79, v83
	v_add_f32_e32 v76, v76, v80
	v_add_f32_e32 v77, v77, v81
	ds_write_b128 v88, v[76:79] offset:16
	ds_read_b128 v[76:79], v88 offset:128
	s_waitcnt lgkmcnt(0)
	v_add_f32_e32 v74, v74, v78
	v_add_f32_e32 v75, v75, v79
	v_add_f32_e32 v72, v72, v76
	v_add_f32_e32 v73, v73, v77
	ds_write_b128 v88, v[72:75] offset:128
	ds_read_b128 v[72:75], v88 offset:144
	s_waitcnt lgkmcnt(0)
	v_add_f32_e32 v70, v70, v74
	v_add_f32_e32 v71, v71, v75
	v_add_f32_e32 v68, v68, v72
	v_add_f32_e32 v69, v69, v73
	ds_write_b128 v88, v[68:71] offset:144
	s_and_b64 exec, exec, s[8:9]
	s_cbranch_execz .LBB0_496
	v_add_f32_e32 v2, v2, v3
	ds_read_b32 v3, v1 offset:256
	s_waitcnt lgkmcnt(0)
	v_add_f32_e32 v2, v2, v3
	ds_write_b32 v1, v2 offset:256
.LBB0_496:
	s_or_b64 exec, exec, s[6:7]
	ds_bpermute_b32 v1, v136, v126
	s_waitcnt lgkmcnt(0)
	v_add_f32_e32 v2, v126, v1
	ds_bpermute_b32 v3, v137, v2
	s_and_saveexec_b64 s[6:7], s[12:13]
	s_cbranch_execz .LBB0_499
	v_mul_lo_u32 v1, v125, s62
	v_add_u32_e32 v1, s61, v1
	v_add_u32_e32 v72, v1, v168
	ds_read_b128 v[68:71], v72
	s_waitcnt lgkmcnt(0)
	v_add_f32_e32 v66, v66, v70
	v_add_f32_e32 v67, v67, v71
	v_add_f32_e32 v64, v64, v68
	v_add_f32_e32 v65, v65, v69
	ds_write_b128 v72, v[64:67]
	ds_read_b128 v[64:67], v72 offset:16
	s_waitcnt lgkmcnt(0)
	v_add_f32_e32 v62, v62, v66
	v_add_f32_e32 v63, v63, v67
	v_add_f32_e32 v60, v60, v64
	v_add_f32_e32 v61, v61, v65
	ds_write_b128 v72, v[60:63] offset:16
	ds_read_b128 v[60:63], v72 offset:128
	s_waitcnt lgkmcnt(0)
	v_add_f32_e32 v58, v58, v62
	v_add_f32_e32 v59, v59, v63
	v_add_f32_e32 v56, v56, v60
	v_add_f32_e32 v57, v57, v61
	ds_write_b128 v72, v[56:59] offset:128
	ds_read_b128 v[56:59], v72 offset:144
	s_waitcnt lgkmcnt(0)
	v_add_f32_e32 v54, v54, v58
	v_add_f32_e32 v55, v55, v59
	v_add_f32_e32 v52, v52, v56
	v_add_f32_e32 v53, v53, v57
	ds_write_b128 v72, v[52:55] offset:144
	s_and_b64 exec, exec, s[8:9]
	s_cbranch_execz .LBB0_499
	v_add_f32_e32 v2, v2, v3
	ds_read_b32 v3, v1 offset:256
	s_waitcnt lgkmcnt(0)
	v_add_f32_e32 v2, v2, v3
	ds_write_b32 v1, v2 offset:256

; #define LAS __attribute__((address_space(3)))
; __device__ __forceinline__ unsigned pk2(float lo, float hi) { const f32x2_t v = {lo, hi}; const bf16x2_t b = __builtin_convertvector(v, bf16x2_t); return __builtin_bit_cast(unsigned, b); }
; template <bool MOBA>
; __device__ __forceinline__ void attn_unit(unsigned char* lds, LAS unsigned char* lds3, const Params& p, int b, int h, int qb) {
;     ...
;             {
; #pragma unroll
;             for (int jb = 0; jb < 2; ++jb) { float ls = 0.f;
; #pragma unroll
;                 for (int kb = 0; kb < 4; ++kb)
; #pragma unroll
;                     for (int r = 0; r < 4; ++r) { const float e = __builtin_amdgcn_exp2f(s[kb][jb][r]); s[kb][jb][r] = e; ls += e; }
;                 lrow[jb] += ls; }
;             { u32x2 vlo[2][4], vhi[2][4];
; #pragma unroll
;             for (int ks2 = 0; ks2 < 2; ++ks2)
; #pragma unroll
;                 for (int db = 0; db < 4; ++db) { const int d = 32 * (db >> 1) + 8 * (fr >> 2) + 4 * (db & 1) + (fr & 3);        const int kx = (32 * ks2 + 4 * fq) ^ (((d >> 3) & 7) << 3);
;                     vlo[ks2][db] = *(const LAS u32x2*)(Vt + slot * 4608 + d * 72 + kx); vhi[ks2][db] = *(const LAS u32x2*)(Vt + slot * 4608 + d * 72 + (kx ^ 16)); }
;             bf16x8 pf[2][2];
; #pragma unroll
;             for (int ks2 = 0; ks2 < 2; ++ks2)
; #pragma unroll
;                 for (int jb = 0; jb < 2; ++jb) { const f32x4 a = s[2 * ks2][jb], c = s[2 * ks2 + 1][jb]; u32x4 pw; pw.x = pk2(a[0], a[1]); pw.y = pk2(a[2], a[3]); pw.z = pk2(c[0], c[1]); pw.w = pk2(c[2], c[3]); pf[ks2][jb] = __builtin_bit_cast(bf16x8, pw); }
;             __builtin_amdgcn_sched_barrier(0);
; #pragma unroll
;             for (int ks2 = 0; ks2 < 2; ++ks2)
; #pragma unroll
;                 for (int db = 0; db < 4; ++db) { u32x4 vv; vv.x = vlo[ks2][db].x; vv.y = vlo[ks2][db].y; vv.z = vhi[ks2][db].x; vv.w = vhi[ks2][db].y; const bf16x8 vf = __builtin_bit_cast(bf16x8, vv);
;                     o[db][0] = __builtin_amdgcn_mfma_f32_16x16x32_bf16(vf, pf[ks2][0], o[db][0], 0, 0, 0); o[db][1] = __builtin_amdgcn_mfma_f32_16x16x32_bf16(vf, pf[ks2][1], o[db][1], 0, 0, 0); }
.LBB0_542:
	v_exp_f32_e32 v145, v102
	v_exp_f32_e32 v144, v86
	v_exp_f32_e32 v147, v103
	v_exp_f32_e32 v146, v87
	v_exp_f32_e32 v149, v104
	v_exp_f32_e32 v148, v88
	v_exp_f32_e32 v151, v105
	v_exp_f32_e32 v150, v89
	v_exp_f32_e32 v153, v98
	v_exp_f32_e32 v152, v82
	v_exp_f32_e32 v154, v83
	v_add_f32_e32 v82, 0, v144
	v_add_f32_e32 v83, 0, v145
	v_exp_f32_e32 v155, v99
	v_add_f32_e32 v82, v146, v82
	v_add_f32_e32 v83, v147, v83
	v_exp_f32_e32 v157, v100
	v_exp_f32_e32 v156, v84
	v_add_f32_e32 v82, v148, v82
	v_add_f32_e32 v83, v149, v83
	v_exp_f32_e32 v159, v101
	v_exp_f32_e32 v158, v85
	v_add_f32_e32 v82, v150, v82
	v_add_f32_e32 v83, v151, v83
	v_exp_f32_e32 v161, v94
	v_exp_f32_e32 v160, v74
	v_add_f32_e32 v82, v152, v82
	v_add_f32_e32 v83, v153, v83
	v_exp_f32_e32 v163, v95
	v_add_f32_e32 v82, v154, v82
	v_add_f32_e32 v83, v155, v83
	v_exp_f32_e32 v162, v75
	v_exp_f32_e32 v165, v96
	v_add_f32_e32 v82, v156, v82
	v_add_f32_e32 v83, v157, v83
	v_exp_f32_e32 v164, v76
	v_exp_f32_e32 v167, v97
	v_add_f32_e32 v82, v158, v82
	v_add_f32_e32 v83, v159, v83
	v_exp_f32_e32 v166, v77
	v_exp_f32_e32 v169, v90
	v_add_f32_e32 v82, v160, v82
	v_add_f32_e32 v83, v161, v83
	v_exp_f32_e32 v168, v78
	v_exp_f32_e32 v171, v91
	v_exp_f32_e32 v170, v79
	v_add_f32_e32 v74, v162, v82
	v_add_f32_e32 v75, v163, v83
	v_exp_f32_e32 v173, v92
	v_exp_f32_e32 v172, v80
	v_add_f32_e32 v74, v164, v74
	v_add_f32_e32 v75, v165, v75
	v_exp_f32_e32 v181, v93
	v_exp_f32_e32 v180, v81
	v_add_f32_e32 v74, v166, v74
	v_add_f32_e32 v75, v167, v75
	s_add_i32 vcc_lo, s94, 0
	v_add_f32_e32 v74, v168, v74
	v_add_f32_e32 v75, v169, v75
	v_add_u32_e32 v90, vcc_lo, v123
	v_add_f32_e32 v74, v170, v74
	v_add_f32_e32 v75, v171, v75
	v_lshlrev_b32_e32 v76, 1, v124
	v_add_f32_e32 v74, v172, v74
	v_add_f32_e32 v75, v173, v75
	v_add_u32_e32 v91, vcc_lo, v125
	v_add_f32_e32 v74, v180, v74
	v_add_f32_e32 v75, v181, v75
	v_add_u32_e32 v98, vcc_lo, v127
	v_add_f32_e32 v110, v110, v74
	v_add_f32_e32 v111, v111, v75
	v_lshlrev_b32_e32 v74, 1, v122
	v_lshlrev_b32_e32 v82, 1, v126
	v_lshlrev_b32_e32 v84, 1, v128
	v_add_u32_e32 v99, vcc_lo, v129
	v_lshlrev_b32_e32 v92, 1, v130
	v_lshlrev_b32_e32 v94, 1, v131
	v_lshlrev_b32_e32 v100, 1, v132
	v_lshlrev_b32_e32 v102, 1, v133
	v_add_u32_e32 v75, v90, v74
	v_add_u32_e32 v77, v90, v76
	v_add_u32_e32 v78, v91, v74
	v_add_u32_e32 v80, v91, v76
	v_add_u32_e32 v83, v98, v82
	v_add_u32_e32 v85, v98, v84
	v_add_u32_e32 v86, v99, v82
	v_add_u32_e32 v88, v99, v84
	v_add_u32_e32 v93, v90, v92
	v_add_u32_e32 v95, v90, v94
	v_add_u32_e32 v96, v91, v92
	v_add_u32_e32 v97, v91, v94
	v_add_u32_e32 v101, v98, v100
	v_add_u32_e32 v103, v98, v102
	v_add_u32_e32 v104, v99, v100
	v_add_u32_e32 v105, v99, v102
	ds_read_b64 v[74:75], v75 offset:36864
	ds_read_b64 v[76:77], v77 offset:36864
	ds_read_b64 v[78:79], v78 offset:36864
	ds_read_b64 v[80:81], v80 offset:36864
	ds_read_b64 v[82:83], v83 offset:36864
	ds_read_b64 v[84:85], v85 offset:36864
	ds_read_b64 v[86:87], v86 offset:36864
	ds_read_b64 v[88:89], v88 offset:36864
	ds_read_b64 v[90:91], v93 offset:36864
	ds_read_b64 v[92:93], v95 offset:36864
	ds_read_b64 v[94:95], v96 offset:36864
	ds_read_b64 v[96:97], v97 offset:36864
	ds_read_b64 v[98:99], v101 offset:36864
	ds_read_b64 v[100:101], v103 offset:36864
	ds_read_b64 v[102:103], v104 offset:36864
	ds_read_b64 v[104:105], v105 offset:36864
	v_cvt_pk_bf16_f32 v140, v145, v147
	v_cvt_pk_bf16_f32 v141, v149, v151
	v_cvt_pk_bf16_f32 v142, v153, v155
	v_cvt_pk_bf16_f32 v143, v157, v159
	v_cvt_pk_bf16_f32 v144, v144, v146
	v_cvt_pk_bf16_f32 v145, v148, v150
	v_cvt_pk_bf16_f32 v146, v152, v154
	v_cvt_pk_bf16_f32 v147, v156, v158
	v_cvt_pk_bf16_f32 v148, v161, v163
	v_cvt_pk_bf16_f32 v149, v165, v167
	v_cvt_pk_bf16_f32 v150, v169, v171
	v_cvt_pk_bf16_f32 v151, v173, v181
	v_cvt_pk_bf16_f32 v152, v160, v162
	v_cvt_pk_bf16_f32 v153, v164, v166
	v_cvt_pk_bf16_f32 v154, v168, v170
	v_cvt_pk_bf16_f32 v155, v172, v180
	s_waitcnt lgkmcnt(14)
	v_mfma_f32_16x16x32_bf16 v[70:73], v[74:77], v[140:143], v[70:73]
	v_mfma_f32_16x16x32_bf16 v[54:57], v[74:77], v[144:147], v[54:57]
	s_waitcnt lgkmcnt(12)
	v_mfma_f32_16x16x32_bf16 v[66:69], v[78:81], v[140:143], v[66:69]
	v_mfma_f32_16x16x32_bf16 v[50:53], v[78:81], v[144:147], v[50:53]
	s_waitcnt lgkmcnt(10)
	v_mfma_f32_16x16x32_bf16 v[62:65], v[82:85], v[140:143], v[62:65]
	v_mfma_f32_16x16x32_bf16 v[46:49], v[82:85], v[144:147], v[46:49]
	s_waitcnt lgkmcnt(8)
	v_mfma_f32_16x16x32_bf16 v[58:61], v[86:89], v[140:143], v[58:61]
	v_mfma_f32_16x16x32_bf16 v[42:45], v[86:89], v[144:147], v[42:45]
	s_waitcnt lgkmcnt(6)
	v_mfma_f32_16x16x32_bf16 v[70:73], v[90:93], v[148:151], v[70:73]
	v_mfma_f32_16x16x32_bf16 v[54:57], v[90:93], v[152:155], v[54:57]
	s_waitcnt lgkmcnt(4)
	v_mfma_f32_16x16x32_bf16 v[66:69], v[94:97], v[148:151], v[66:69]
	v_mfma_f32_16x16x32_bf16 v[50:53], v[94:97], v[152:155], v[50:53]
	s_waitcnt lgkmcnt(2)
	v_mfma_f32_16x16x32_bf16 v[62:65], v[98:101], v[148:151], v[62:65]
	v_mfma_f32_16x16x32_bf16 v[46:49], v[98:101], v[152:155], v[46:49]
	s_waitcnt lgkmcnt(0)
	v_mfma_f32_16x16x32_bf16 v[58:61], v[102:105], v[148:151], v[58:61]
	v_mfma_f32_16x16x32_bf16 v[42:45], v[102:105], v[152:155], v[42:45]

; #define LAS __attribute__((address_space(3)))
; __device__ __forceinline__ unsigned pk2(float lo, float hi) { const f32x2_t v = {lo, hi}; const bf16x2_t b = __builtin_convertvector(v, bf16x2_t); return __builtin_bit_cast(unsigned, b); }
; template <bool MOBA>
; __device__ __forceinline__ void attn_unit(unsigned char* lds, LAS unsigned char* lds3, const Params& p, int b, int h, int qb) {
;     ...
;             {
; #pragma unroll
;             for (int jb = 0; jb < 2; ++jb) { float ls = 0.f;
; #pragma unroll
;                 for (int kb = 0; kb < 4; ++kb)
; #pragma unroll
;                     for (int r = 0; r < 4; ++r) { const float e = __builtin_amdgcn_exp2f(s[kb][jb][r]); s[kb][jb][r] = e; ls += e; }
;                 lrow[jb] += ls; }
;             { u32x2 vlo[2][4], vhi[2][4];
; #pragma unroll
;             for (int ks2 = 0; ks2 < 2; ++ks2)
; #pragma unroll
;                 for (int db = 0; db < 4; ++db) { const int d = 32 * (db >> 1) + 8 * (fr >> 2) + 4 * (db & 1) + (fr & 3);        const int kx = (32 * ks2 + 4 * fq) ^ (((d >> 3) & 7) << 3);
;                     vlo[ks2][db] = *(const LAS u32x2*)(Vt + slot * 4608 + d * 72 + kx); vhi[ks2][db] = *(const LAS u32x2*)(Vt + slot * 4608 + d * 72 + (kx ^ 16)); }
;             bf16x8 pf[2][2];
; #pragma unroll
;             for (int ks2 = 0; ks2 < 2; ++ks2)
; #pragma unroll
;                 for (int jb = 0; jb < 2; ++jb) { const f32x4 a = s[2 * ks2][jb], c = s[2 * ks2 + 1][jb]; u32x4 pw; pw.x = pk2(a[0], a[1]); pw.y = pk2(a[2], a[3]); pw.z = pk2(c[0], c[1]); pw.w = pk2(c[2], c[3]); pf[ks2][jb] = __builtin_bit_cast(bf16x8, pw); }
;             __builtin_amdgcn_sched_barrier(0);
; #pragma unroll
;             for (int ks2 = 0; ks2 < 2; ++ks2)
; #pragma unroll
;                 for (int db = 0; db < 4; ++db) { u32x4 vv; vv.x = vlo[ks2][db].x; vv.y = vlo[ks2][db].y; vv.z = vhi[ks2][db].x; vv.w = vhi[ks2][db].y; const bf16x8 vf = __builtin_bit_cast(bf16x8, vv);
;                     o[db][0] = __builtin_amdgcn_mfma_f32_16x16x32_bf16(vf, pf[ks2][0], o[db][0], 0, 0, 0); o[db][1] = __builtin_amdgcn_mfma_f32_16x16x32_bf16(vf, pf[ks2][1], o[db][1], 0, 0, 0); }
.LBB0_549:
	v_exp_f32_e32 v143, v102
	v_exp_f32_e32 v142, v86
	v_exp_f32_e32 v145, v103
	v_exp_f32_e32 v144, v87
	v_exp_f32_e32 v147, v104
	v_exp_f32_e32 v146, v88
	v_exp_f32_e32 v149, v105
	v_exp_f32_e32 v148, v89
	v_exp_f32_e32 v151, v98
	v_exp_f32_e32 v150, v78
	v_exp_f32_e32 v152, v79
	v_add_f32_e32 v78, 0, v142
	v_add_f32_e32 v79, 0, v143
	v_exp_f32_e32 v153, v99
	v_add_f32_e32 v78, v144, v78
	v_add_f32_e32 v79, v145, v79
	v_exp_f32_e32 v155, v100
	v_exp_f32_e32 v154, v80
	v_add_f32_e32 v78, v146, v78
	v_add_f32_e32 v79, v147, v79
	v_exp_f32_e32 v157, v101
	v_add_f32_e32 v78, v148, v78
	v_add_f32_e32 v79, v149, v79
	v_exp_f32_e32 v156, v81
	v_exp_f32_e32 v159, v94
	v_add_f32_e32 v78, v150, v78
	v_add_f32_e32 v79, v151, v79
	v_exp_f32_e32 v158, v74
	v_exp_f32_e32 v161, v95
	v_add_f32_e32 v78, v152, v78
	v_add_f32_e32 v79, v153, v79
	v_exp_f32_e32 v160, v75
	v_exp_f32_e32 v163, v96
	v_add_f32_e32 v78, v154, v78
	v_add_f32_e32 v79, v155, v79
	v_exp_f32_e32 v162, v76
	v_exp_f32_e32 v165, v97
	v_exp_f32_e32 v164, v77
	v_add_f32_e32 v74, v156, v78
	v_add_f32_e32 v75, v157, v79
	v_exp_f32_e32 v167, v90
	v_exp_f32_e32 v166, v82
	v_add_f32_e32 v74, v158, v74
	v_add_f32_e32 v75, v159, v75
	v_exp_f32_e32 v169, v91
	v_exp_f32_e32 v168, v83
	v_add_f32_e32 v74, v160, v74
	v_add_f32_e32 v75, v161, v75
	v_exp_f32_e32 v171, v92
	v_exp_f32_e32 v170, v84
	v_add_f32_e32 v74, v162, v74
	v_add_f32_e32 v75, v163, v75
	v_exp_f32_e32 v173, v93
	v_exp_f32_e32 v172, v85
	v_add_f32_e32 v74, v164, v74
	v_add_f32_e32 v75, v165, v75
	s_add_i32 s84, s94, 0
	v_add_f32_e32 v74, v166, v74
	v_add_f32_e32 v75, v167, v75
	v_add_u32_e32 v1, s84, v123
	v_add_f32_e32 v74, v168, v74
	v_add_f32_e32 v75, v169, v75
	v_lshlrev_b32_e32 v76, 1, v124
	v_add_f32_e32 v74, v170, v74
	v_add_f32_e32 v75, v171, v75
	v_add_u32_e32 v90, s84, v125
	v_add_f32_e32 v74, v172, v74
	v_add_f32_e32 v75, v173, v75
	v_add_u32_e32 v98, s84, v127
	v_add_f32_e32 v110, v110, v74
	v_add_f32_e32 v111, v111, v75
	v_lshlrev_b32_e32 v74, 1, v122
	v_lshlrev_b32_e32 v82, 1, v126
	v_lshlrev_b32_e32 v84, 1, v128
	v_add_u32_e32 v99, s84, v129
	v_lshlrev_b32_e32 v91, 1, v130
	v_lshlrev_b32_e32 v93, 1, v131
	v_add_u32_e32 v75, v1, v74
	v_add_u32_e32 v77, v1, v76
	v_add_u32_e32 v78, v90, v74
	v_add_u32_e32 v80, v90, v76
	v_add_u32_e32 v83, v98, v82
	v_add_u32_e32 v85, v98, v84
	v_add_u32_e32 v86, v99, v82
	v_add_u32_e32 v88, v99, v84
	v_add_u32_e32 v92, v1, v91
	v_add_u32_e32 v1, v1, v93
	v_add_u32_e32 v94, v90, v91
	v_add_u32_e32 v96, v90, v93
	ds_read_b64 v[74:75], v75 offset:46080
	ds_read_b64 v[76:77], v77 offset:46080
	ds_read_b64 v[78:79], v78 offset:46080
	ds_read_b64 v[80:81], v80 offset:46080
	ds_read_b64 v[82:83], v83 offset:46080
	ds_read_b64 v[84:85], v85 offset:46080
	ds_read_b64 v[86:87], v86 offset:46080
	ds_read_b64 v[88:89], v88 offset:46080
	ds_read_b64 v[90:91], v92 offset:46080
	ds_read_b64 v[92:93], v1 offset:46080
	ds_read_b64 v[94:95], v94 offset:46080
	ds_read_b64 v[96:97], v96 offset:46080
	v_lshlrev_b32_e32 v1, 1, v132
	v_lshlrev_b32_e32 v101, 1, v133
	v_add_u32_e32 v100, v98, v1
	v_add_u32_e32 v102, v98, v101
	v_add_u32_e32 v104, v99, v101
	v_add_u32_e32 v1, v99, v1
	ds_read_b64 v[98:99], v100 offset:46080
	ds_read_b64 v[100:101], v102 offset:46080
	ds_read_b64 v[102:103], v1 offset:46080
	ds_read_b64 v[104:105], v104 offset:46080
	v_cvt_pk_bf16_f32 v138, v143, v145
	v_cvt_pk_bf16_f32 v139, v147, v149
	v_cvt_pk_bf16_f32 v140, v151, v153
	v_cvt_pk_bf16_f32 v141, v155, v157
	v_cvt_pk_bf16_f32 v142, v142, v144
	v_cvt_pk_bf16_f32 v143, v146, v148
	v_cvt_pk_bf16_f32 v144, v150, v152
	v_cvt_pk_bf16_f32 v145, v154, v156
	v_cvt_pk_bf16_f32 v146, v159, v161
	v_cvt_pk_bf16_f32 v147, v163, v165
	v_cvt_pk_bf16_f32 v148, v167, v169
	v_cvt_pk_bf16_f32 v149, v171, v173
	v_cvt_pk_bf16_f32 v150, v158, v160
	v_cvt_pk_bf16_f32 v151, v162, v164
	v_cvt_pk_bf16_f32 v152, v166, v168
	v_cvt_pk_bf16_f32 v153, v170, v172
	s_waitcnt lgkmcnt(14)
	v_mfma_f32_16x16x32_bf16 v[70:73], v[74:77], v[138:141], v[70:73]
	v_mfma_f32_16x16x32_bf16 v[54:57], v[74:77], v[142:145], v[54:57]
	s_waitcnt lgkmcnt(12)
	v_mfma_f32_16x16x32_bf16 v[66:69], v[78:81], v[138:141], v[66:69]
	v_mfma_f32_16x16x32_bf16 v[50:53], v[78:81], v[142:145], v[50:53]
	s_waitcnt lgkmcnt(10)
	v_mfma_f32_16x16x32_bf16 v[62:65], v[82:85], v[138:141], v[62:65]
	v_mfma_f32_16x16x32_bf16 v[46:49], v[82:85], v[142:145], v[46:49]
	s_waitcnt lgkmcnt(8)
	v_mfma_f32_16x16x32_bf16 v[58:61], v[86:89], v[138:141], v[58:61]
	v_mfma_f32_16x16x32_bf16 v[42:45], v[86:89], v[142:145], v[42:45]
	s_waitcnt lgkmcnt(6)
	v_mfma_f32_16x16x32_bf16 v[70:73], v[90:93], v[146:149], v[70:73]
	v_mfma_f32_16x16x32_bf16 v[54:57], v[90:93], v[150:153], v[54:57]
	s_waitcnt lgkmcnt(4)
	v_mfma_f32_16x16x32_bf16 v[66:69], v[94:97], v[146:149], v[66:69]
	v_mfma_f32_16x16x32_bf16 v[50:53], v[94:97], v[150:153], v[50:53]
	s_waitcnt lgkmcnt(2)
	v_mfma_f32_16x16x32_bf16 v[62:65], v[98:101], v[146:149], v[62:65]
	v_mfma_f32_16x16x32_bf16 v[46:49], v[98:101], v[150:153], v[46:49]
	s_waitcnt lgkmcnt(0)
	v_mfma_f32_16x16x32_bf16 v[58:61], v[102:105], v[146:149], v[58:61]
	v_mfma_f32_16x16x32_bf16 v[42:45], v[102:105], v[150:153], v[42:45]
	s_andn2_b64 vcc, exec, s[86:87]
	s_cbranch_vccz .LBB0_554
